# RWKV scan: rows swapped in odd quads so both rows reduce in one DPP chain (9 DPP per step), packed f32 update
# baseline (speedup 1.0000x reference)
.LBB0_183:
	s_ashr_i32 s2, s16, 1
	s_ashr_i32 s3, s2, 31
	s_lshl_b64 s[2:3], s[2:3], 14
	v_lshl_add_u64 v[80:81], v[114:115], 0, s[2:3]
	v_mov_b32_e32 v79, 0
	v_lshlrev_b32_e32 v78, 8, v77
	v_lshl_add_u64 v[42:43], v[78:79], 0, v[80:81]
	global_store_dwordx4 v[42:43], v[20:23], off
	v_lshlrev_b32_e32 v78, 8, v40
	v_lshl_add_u64 v[44:45], v[78:79], 0, v[80:81]
	global_store_dwordx4 v[44:45], v[24:27], off
	s_waitcnt lgkmcnt(0)
	s_barrier

.LBB0_203:
	s_andn2_saveexec_b64 s[0:1], s[8:9]
	s_cbranch_execz .LBB0_184
	s_waitcnt lgkmcnt(0)
	s_barrier
	v_readlane_b32 s2, v251, 27
	v_and_b32_e32 v78, 15, v0
	v_lshrrev_b32_e32 v79, 4, v0
	s_nop 1
	v_lshl_add_u32 v103, v78, 4, s2
	v_bfe_u32 v81, v78, 2, 1
	v_lshlrev_b32_e32 v80, 1, v79
	v_add_u32_e32 v80, v80, v81
	v_lshl_add_u32 v77, s17, 5, v80
	v_xor_b32_e32 v40, 1, v77
	v_lshl_add_u32 v75, v77, 3, s2
	v_add_u32_e32 v75, 0xa000, v75
	v_lshl_add_u32 v37, v40, 3, s2
	v_add_u32_e32 v37, 0xa000, v37
	v_lshl_add_u32 v80, v80, 2, s2
	v_add_u32_e32 v80, 0x1c000, v80
	v_lshl_add_u32 v79, v0, 2, s2
	v_add_u32_e32 v79, 0x1e000, v79
	v_and_b32_e32 v81, 11, v78
	v_cmp_eq_u32_e32 vcc, 0, v81
	s_nop 3
	v_cndmask_b32_e32 v76, v79, v80, vcc
	v_mov_b32_e32 v20, 0
	v_mov_b32_e32 v21, 0
	v_mov_b32_e32 v22, 0
	v_mov_b32_e32 v23, 0
	v_mov_b32_e32 v24, 0
	v_mov_b32_e32 v25, 0
	v_mov_b32_e32 v26, 0
	v_mov_b32_e32 v27, 0
	s_setprio 3
	s_mov_b32 s8, 0
	s_waitcnt vmcnt(0)
.Lrw_scan_loop:
	s_and_b32 s2, s8, 1
	s_mul_i32 s3, s2, 0xe000
	s_lshl_b32 s2, s2, 12
	v_add_u32_e32 v195, s3, v103
	v_add_u32_e32 v196, s3, v75
	v_add_u32_e32 v36, s3, v37
	v_add_u32_e32 v102, s2, v76
	ds_read_b128 v[140:143], v195 offset:0
	ds_read_b128 v[152:155], v195 offset:32768
	ds_read_b128 v[164:167], v195 offset:24576
	ds_read_b128 v[176:179], v195 offset:16384
	ds_read_b128 v[84:87], v195 offset:8192
	ds_read_b64 v[4:5], v196 offset:0
	ds_read_b64 v[6:7], v36 offset:0
	ds_read_b128 v[144:147], v195 offset:256
	ds_read_b128 v[156:159], v195 offset:33024
	ds_read_b128 v[168:171], v195 offset:24832
	ds_read_b128 v[180:183], v195 offset:16640
	ds_read_b128 v[88:91], v195 offset:8448
	ds_read_b64 v[8:9], v196 offset:512
	ds_read_b64 v[10:11], v36 offset:512
	ds_read_b128 v[148:151], v195 offset:512
	ds_read_b128 v[160:163], v195 offset:33280
	ds_read_b128 v[172:175], v195 offset:25088
	ds_read_b128 v[184:187], v195 offset:16896
	ds_read_b128 v[92:95], v195 offset:8704
	ds_read_b64 v[12:13], v196 offset:1024
	ds_read_b64 v[14:15], v36 offset:1024
	s_waitcnt lgkmcnt(14)
	v_mul_f32_e32 v34, v24, v140
	v_mul_f32_e32 v38, v24, v152
	v_mul_f32_e32 v33, v20, v140
	v_mul_f32_e32 v35, v20, v152
	v_fmac_f32_e32 v34, v25, v141
	v_fmac_f32_e32 v38, v25, v153
	v_fmac_f32_e32 v33, v21, v141
	v_fmac_f32_e32 v35, v21, v153
	v_fmac_f32_e32 v34, v26, v142
	v_fmac_f32_e32 v38, v26, v154
	v_fmac_f32_e32 v33, v22, v142
	v_fmac_f32_e32 v35, v22, v154
	v_fmac_f32_e32 v34, v27, v143
	v_fmac_f32_e32 v38, v27, v155
	v_fmac_f32_e32 v33, v23, v143
	v_fmac_f32_e32 v35, v23, v155
	v_add_f32_dpp v28, v34, v33 row_half_mirror row_mask:0xf bank_mask:0xf
	v_add_f32_dpp v32, v38, v35 row_half_mirror row_mask:0xf bank_mask:0xf
	v_pk_mul_f32 v[20:21], v[20:21], v[164:165]
	v_add_f32_dpp v28, v28, v28 row_ror:8 row_mask:0xf bank_mask:0xf
	v_add_f32_dpp v32, v32, v32 row_ror:8 row_mask:0xf bank_mask:0xf
	v_pk_mul_f32 v[22:23], v[22:23], v[166:167]
	v_add_f32_dpp v28, v28, v28 quad_perm:[1,0,3,2] row_mask:0xf bank_mask:0xf
	v_add_f32_dpp v32, v32, v32 quad_perm:[1,0,3,2] row_mask:0xf bank_mask:0xf
	v_pk_mul_f32 v[24:25], v[24:25], v[164:165]
	v_add_f32_dpp v28, v28, v28 quad_perm:[2,3,0,1] row_mask:0xf bank_mask:0xf
	v_add_f32_dpp v32, v32, v32 quad_perm:[2,3,0,1] row_mask:0xf bank_mask:0xf
	v_pk_mul_f32 v[26:27], v[26:27], v[166:167]
	v_pk_fma_f32 v[20:21], v[176:177], v[4:5], v[20:21] op_sel_hi:[1,0,1]
	v_mov_b32_dpp v30, v28 row_half_mirror row_mask:0xf bank_mask:0xf
	v_pk_fma_f32 v[22:23], v[178:179], v[4:5], v[22:23] op_sel_hi:[1,0,1]
	v_pk_fma_f32 v[24:25], v[176:177], v[6:7], v[24:25] op_sel_hi:[1,0,1]
	v_pk_fma_f32 v[26:27], v[178:179], v[6:7], v[26:27] op_sel_hi:[1,0,1]
	v_pk_fma_f32 v[20:21], v[84:85], v[28:29], v[20:21] op_sel_hi:[1,0,1] neg_lo:[0,1,0] neg_hi:[0,1,0]
	v_pk_fma_f32 v[22:23], v[86:87], v[28:29], v[22:23] op_sel_hi:[1,0,1] neg_lo:[0,1,0] neg_hi:[0,1,0]
	v_pk_fma_f32 v[24:25], v[84:85], v[30:31], v[24:25] op_sel_hi:[1,0,1] neg_lo:[0,1,0] neg_hi:[0,1,0]
	v_pk_fma_f32 v[26:27], v[86:87], v[30:31], v[26:27] op_sel_hi:[1,0,1] neg_lo:[0,1,0] neg_hi:[0,1,0]
	v_add_f32_e32 v39, v32, v5
	ds_write_b32 v102, v39 offset:0
	ds_read_b128 v[140:143], v195 offset:768
	ds_read_b128 v[152:155], v195 offset:33536
	ds_read_b128 v[164:167], v195 offset:25344
	ds_read_b128 v[176:179], v195 offset:17152
	ds_read_b128 v[84:87], v195 offset:8960
	ds_read_b64 v[4:5], v196 offset:1536
	ds_read_b64 v[6:7], v36 offset:1536
	s_waitcnt lgkmcnt(15)
	v_mul_f32_e32 v34, v24, v144
	v_mul_f32_e32 v38, v24, v156
	v_mul_f32_e32 v33, v20, v144
	v_mul_f32_e32 v35, v20, v156
	v_fmac_f32_e32 v34, v25, v145
	v_fmac_f32_e32 v38, v25, v157
	v_fmac_f32_e32 v33, v21, v145
	v_fmac_f32_e32 v35, v21, v157
	v_fmac_f32_e32 v34, v26, v146
	v_fmac_f32_e32 v38, v26, v158
	v_fmac_f32_e32 v33, v22, v146
	v_fmac_f32_e32 v35, v22, v158
	v_fmac_f32_e32 v34, v27, v147
	v_fmac_f32_e32 v38, v27, v159
	v_fmac_f32_e32 v33, v23, v147
	v_fmac_f32_e32 v35, v23, v159
	v_add_f32_dpp v28, v34, v33 row_half_mirror row_mask:0xf bank_mask:0xf
	v_add_f32_dpp v32, v38, v35 row_half_mirror row_mask:0xf bank_mask:0xf
	v_pk_mul_f32 v[20:21], v[20:21], v[168:169]
	v_add_f32_dpp v28, v28, v28 row_ror:8 row_mask:0xf bank_mask:0xf
	v_add_f32_dpp v32, v32, v32 row_ror:8 row_mask:0xf bank_mask:0xf
	v_pk_mul_f32 v[22:23], v[22:23], v[170:171]
	v_add_f32_dpp v28, v28, v28 quad_perm:[1,0,3,2] row_mask:0xf bank_mask:0xf
	v_add_f32_dpp v32, v32, v32 quad_perm:[1,0,3,2] row_mask:0xf bank_mask:0xf
	v_pk_mul_f32 v[24:25], v[24:25], v[168:169]
	v_add_f32_dpp v28, v28, v28 quad_perm:[2,3,0,1] row_mask:0xf bank_mask:0xf
	v_add_f32_dpp v32, v32, v32 quad_perm:[2,3,0,1] row_mask:0xf bank_mask:0xf
	v_pk_mul_f32 v[26:27], v[26:27], v[170:171]
	v_pk_fma_f32 v[20:21], v[180:181], v[8:9], v[20:21] op_sel_hi:[1,0,1]
	v_mov_b32_dpp v30, v28 row_half_mirror row_mask:0xf bank_mask:0xf
	v_pk_fma_f32 v[22:23], v[182:183], v[8:9], v[22:23] op_sel_hi:[1,0,1]
	v_pk_fma_f32 v[24:25], v[180:181], v[10:11], v[24:25] op_sel_hi:[1,0,1]
	v_pk_fma_f32 v[26:27], v[182:183], v[10:11], v[26:27] op_sel_hi:[1,0,1]
	v_pk_fma_f32 v[20:21], v[88:89], v[28:29], v[20:21] op_sel_hi:[1,0,1] neg_lo:[0,1,0] neg_hi:[0,1,0]
	v_pk_fma_f32 v[22:23], v[90:91], v[28:29], v[22:23] op_sel_hi:[1,0,1] neg_lo:[0,1,0] neg_hi:[0,1,0]
	v_pk_fma_f32 v[24:25], v[88:89], v[30:31], v[24:25] op_sel_hi:[1,0,1] neg_lo:[0,1,0] neg_hi:[0,1,0]
	v_pk_fma_f32 v[26:27], v[90:91], v[30:31], v[26:27] op_sel_hi:[1,0,1] neg_lo:[0,1,0] neg_hi:[0,1,0]
	v_add_f32_e32 v39, v32, v9
	ds_write_b32 v102, v39 offset:128
	ds_read_b128 v[144:147], v195 offset:1024
	ds_read_b128 v[156:159], v195 offset:33792
	ds_read_b128 v[168:171], v195 offset:25600
	ds_read_b128 v[180:183], v195 offset:17408
	ds_read_b128 v[88:91], v195 offset:9216
	ds_read_b64 v[8:9], v196 offset:2048
	ds_read_b64 v[10:11], v36 offset:2048
	s_waitcnt lgkmcnt(15)
	v_mul_f32_e32 v34, v24, v148
	v_mul_f32_e32 v38, v24, v160
	v_mul_f32_e32 v33, v20, v148
	v_mul_f32_e32 v35, v20, v160
	v_fmac_f32_e32 v34, v25, v149
	v_fmac_f32_e32 v38, v25, v161
	v_fmac_f32_e32 v33, v21, v149
	v_fmac_f32_e32 v35, v21, v161
	v_fmac_f32_e32 v34, v26, v150
	v_fmac_f32_e32 v38, v26, v162
	v_fmac_f32_e32 v33, v22, v150
	v_fmac_f32_e32 v35, v22, v162
	v_fmac_f32_e32 v34, v27, v151
	v_fmac_f32_e32 v38, v27, v163
	v_fmac_f32_e32 v33, v23, v151
	v_fmac_f32_e32 v35, v23, v163
	v_add_f32_dpp v28, v34, v33 row_half_mirror row_mask:0xf bank_mask:0xf
	v_add_f32_dpp v32, v38, v35 row_half_mirror row_mask:0xf bank_mask:0xf
	v_pk_mul_f32 v[20:21], v[20:21], v[172:173]
	v_add_f32_dpp v28, v28, v28 row_ror:8 row_mask:0xf bank_mask:0xf
	v_add_f32_dpp v32, v32, v32 row_ror:8 row_mask:0xf bank_mask:0xf
	v_pk_mul_f32 v[22:23], v[22:23], v[174:175]
	v_add_f32_dpp v28, v28, v28 quad_perm:[1,0,3,2] row_mask:0xf bank_mask:0xf
	v_add_f32_dpp v32, v32, v32 quad_perm:[1,0,3,2] row_mask:0xf bank_mask:0xf
	v_pk_mul_f32 v[24:25], v[24:25], v[172:173]
	v_add_f32_dpp v28, v28, v28 quad_perm:[2,3,0,1] row_mask:0xf bank_mask:0xf
	v_add_f32_dpp v32, v32, v32 quad_perm:[2,3,0,1] row_mask:0xf bank_mask:0xf
	v_pk_mul_f32 v[26:27], v[26:27], v[174:175]
	v_pk_fma_f32 v[20:21], v[184:185], v[12:13], v[20:21] op_sel_hi:[1,0,1]
	v_mov_b32_dpp v30, v28 row_half_mirror row_mask:0xf bank_mask:0xf
	v_pk_fma_f32 v[22:23], v[186:187], v[12:13], v[22:23] op_sel_hi:[1,0,1]
	v_pk_fma_f32 v[24:25], v[184:185], v[14:15], v[24:25] op_sel_hi:[1,0,1]
	v_pk_fma_f32 v[26:27], v[186:187], v[14:15], v[26:27] op_sel_hi:[1,0,1]
	v_pk_fma_f32 v[20:21], v[92:93], v[28:29], v[20:21] op_sel_hi:[1,0,1] neg_lo:[0,1,0] neg_hi:[0,1,0]
	v_pk_fma_f32 v[22:23], v[94:95], v[28:29], v[22:23] op_sel_hi:[1,0,1] neg_lo:[0,1,0] neg_hi:[0,1,0]
	v_pk_fma_f32 v[24:25], v[92:93], v[30:31], v[24:25] op_sel_hi:[1,0,1] neg_lo:[0,1,0] neg_hi:[0,1,0]
	v_pk_fma_f32 v[26:27], v[94:95], v[30:31], v[26:27] op_sel_hi:[1,0,1] neg_lo:[0,1,0] neg_hi:[0,1,0]
	v_add_f32_e32 v39, v32, v13
	ds_write_b32 v102, v39 offset:256
	ds_read_b128 v[148:151], v195 offset:1280
	ds_read_b128 v[160:163], v195 offset:34048
	ds_read_b128 v[172:175], v195 offset:25856
	ds_read_b128 v[184:187], v195 offset:17664
	ds_read_b128 v[92:95], v195 offset:9472
	ds_read_b64 v[12:13], v196 offset:2560
	ds_read_b64 v[14:15], v36 offset:2560
	s_waitcnt lgkmcnt(15)
	v_mul_f32_e32 v34, v24, v140
	v_mul_f32_e32 v38, v24, v152
	v_mul_f32_e32 v33, v20, v140
	v_mul_f32_e32 v35, v20, v152
	v_fmac_f32_e32 v34, v25, v141
	v_fmac_f32_e32 v38, v25, v153
	v_fmac_f32_e32 v33, v21, v141
	v_fmac_f32_e32 v35, v21, v153
	v_fmac_f32_e32 v34, v26, v142
	v_fmac_f32_e32 v38, v26, v154
	v_fmac_f32_e32 v33, v22, v142
	v_fmac_f32_e32 v35, v22, v154
	v_fmac_f32_e32 v34, v27, v143
	v_fmac_f32_e32 v38, v27, v155
	v_fmac_f32_e32 v33, v23, v143
	v_fmac_f32_e32 v35, v23, v155
	v_add_f32_dpp v28, v34, v33 row_half_mirror row_mask:0xf bank_mask:0xf
	v_add_f32_dpp v32, v38, v35 row_half_mirror row_mask:0xf bank_mask:0xf
	v_pk_mul_f32 v[20:21], v[20:21], v[164:165]
	v_add_f32_dpp v28, v28, v28 row_ror:8 row_mask:0xf bank_mask:0xf
	v_add_f32_dpp v32, v32, v32 row_ror:8 row_mask:0xf bank_mask:0xf
	v_pk_mul_f32 v[22:23], v[22:23], v[166:167]
	v_add_f32_dpp v28, v28, v28 quad_perm:[1,0,3,2] row_mask:0xf bank_mask:0xf
	v_add_f32_dpp v32, v32, v32 quad_perm:[1,0,3,2] row_mask:0xf bank_mask:0xf
	v_pk_mul_f32 v[24:25], v[24:25], v[164:165]
	v_add_f32_dpp v28, v28, v28 quad_perm:[2,3,0,1] row_mask:0xf bank_mask:0xf
	v_add_f32_dpp v32, v32, v32 quad_perm:[2,3,0,1] row_mask:0xf bank_mask:0xf
	v_pk_mul_f32 v[26:27], v[26:27], v[166:167]
	v_pk_fma_f32 v[20:21], v[176:177], v[4:5], v[20:21] op_sel_hi:[1,0,1]
	v_mov_b32_dpp v30, v28 row_half_mirror row_mask:0xf bank_mask:0xf
	v_pk_fma_f32 v[22:23], v[178:179], v[4:5], v[22:23] op_sel_hi:[1,0,1]
	v_pk_fma_f32 v[24:25], v[176:177], v[6:7], v[24:25] op_sel_hi:[1,0,1]
	v_pk_fma_f32 v[26:27], v[178:179], v[6:7], v[26:27] op_sel_hi:[1,0,1]
	v_pk_fma_f32 v[20:21], v[84:85], v[28:29], v[20:21] op_sel_hi:[1,0,1] neg_lo:[0,1,0] neg_hi:[0,1,0]
	v_pk_fma_f32 v[22:23], v[86:87], v[28:29], v[22:23] op_sel_hi:[1,0,1] neg_lo:[0,1,0] neg_hi:[0,1,0]
	v_pk_fma_f32 v[24:25], v[84:85], v[30:31], v[24:25] op_sel_hi:[1,0,1] neg_lo:[0,1,0] neg_hi:[0,1,0]
	v_pk_fma_f32 v[26:27], v[86:87], v[30:31], v[26:27] op_sel_hi:[1,0,1] neg_lo:[0,1,0] neg_hi:[0,1,0]
	v_add_f32_e32 v39, v32, v5
	ds_write_b32 v102, v39 offset:384
	ds_read_b128 v[140:143], v195 offset:1536
	ds_read_b128 v[152:155], v195 offset:34304
	ds_read_b128 v[164:167], v195 offset:26112
	ds_read_b128 v[176:179], v195 offset:17920
	ds_read_b128 v[84:87], v195 offset:9728
	ds_read_b64 v[4:5], v196 offset:3072
	ds_read_b64 v[6:7], v36 offset:3072
	s_waitcnt lgkmcnt(15)
	v_mul_f32_e32 v34, v24, v144
	v_mul_f32_e32 v38, v24, v156
	v_mul_f32_e32 v33, v20, v144
	v_mul_f32_e32 v35, v20, v156
	v_fmac_f32_e32 v34, v25, v145
	v_fmac_f32_e32 v38, v25, v157
	v_fmac_f32_e32 v33, v21, v145
	v_fmac_f32_e32 v35, v21, v157
	v_fmac_f32_e32 v34, v26, v146
	v_fmac_f32_e32 v38, v26, v158
	v_fmac_f32_e32 v33, v22, v146
	v_fmac_f32_e32 v35, v22, v158
	v_fmac_f32_e32 v34, v27, v147
	v_fmac_f32_e32 v38, v27, v159
	v_fmac_f32_e32 v33, v23, v147
	v_fmac_f32_e32 v35, v23, v159
	v_add_f32_dpp v28, v34, v33 row_half_mirror row_mask:0xf bank_mask:0xf
	v_add_f32_dpp v32, v38, v35 row_half_mirror row_mask:0xf bank_mask:0xf
	v_pk_mul_f32 v[20:21], v[20:21], v[168:169]
	v_add_f32_dpp v28, v28, v28 row_ror:8 row_mask:0xf bank_mask:0xf
	v_add_f32_dpp v32, v32, v32 row_ror:8 row_mask:0xf bank_mask:0xf
	v_pk_mul_f32 v[22:23], v[22:23], v[170:171]
	v_add_f32_dpp v28, v28, v28 quad_perm:[1,0,3,2] row_mask:0xf bank_mask:0xf
	v_add_f32_dpp v32, v32, v32 quad_perm:[1,0,3,2] row_mask:0xf bank_mask:0xf
	v_pk_mul_f32 v[24:25], v[24:25], v[168:169]
	v_add_f32_dpp v28, v28, v28 quad_perm:[2,3,0,1] row_mask:0xf bank_mask:0xf
	v_add_f32_dpp v32, v32, v32 quad_perm:[2,3,0,1] row_mask:0xf bank_mask:0xf
	v_pk_mul_f32 v[26:27], v[26:27], v[170:171]
	v_pk_fma_f32 v[20:21], v[180:181], v[8:9], v[20:21] op_sel_hi:[1,0,1]
	v_mov_b32_dpp v30, v28 row_half_mirror row_mask:0xf bank_mask:0xf
	v_pk_fma_f32 v[22:23], v[182:183], v[8:9], v[22:23] op_sel_hi:[1,0,1]
	v_pk_fma_f32 v[24:25], v[180:181], v[10:11], v[24:25] op_sel_hi:[1,0,1]
	v_pk_fma_f32 v[26:27], v[182:183], v[10:11], v[26:27] op_sel_hi:[1,0,1]
	v_pk_fma_f32 v[20:21], v[88:89], v[28:29], v[20:21] op_sel_hi:[1,0,1] neg_lo:[0,1,0] neg_hi:[0,1,0]
	v_pk_fma_f32 v[22:23], v[90:91], v[28:29], v[22:23] op_sel_hi:[1,0,1] neg_lo:[0,1,0] neg_hi:[0,1,0]
	v_pk_fma_f32 v[24:25], v[88:89], v[30:31], v[24:25] op_sel_hi:[1,0,1] neg_lo:[0,1,0] neg_hi:[0,1,0]
	v_pk_fma_f32 v[26:27], v[90:91], v[30:31], v[26:27] op_sel_hi:[1,0,1] neg_lo:[0,1,0] neg_hi:[0,1,0]
	v_add_f32_e32 v39, v32, v9
	ds_write_b32 v102, v39 offset:512
	ds_read_b128 v[144:147], v195 offset:1792
	ds_read_b128 v[156:159], v195 offset:34560
	ds_read_b128 v[168:171], v195 offset:26368
	ds_read_b128 v[180:183], v195 offset:18176
	ds_read_b128 v[88:91], v195 offset:9984
	ds_read_b64 v[8:9], v196 offset:3584
	ds_read_b64 v[10:11], v36 offset:3584
	s_waitcnt lgkmcnt(15)
	v_mul_f32_e32 v34, v24, v148
	v_mul_f32_e32 v38, v24, v160
	v_mul_f32_e32 v33, v20, v148
	v_mul_f32_e32 v35, v20, v160
	v_fmac_f32_e32 v34, v25, v149
	v_fmac_f32_e32 v38, v25, v161
	v_fmac_f32_e32 v33, v21, v149
	v_fmac_f32_e32 v35, v21, v161
	v_fmac_f32_e32 v34, v26, v150
	v_fmac_f32_e32 v38, v26, v162
	v_fmac_f32_e32 v33, v22, v150
	v_fmac_f32_e32 v35, v22, v162
	v_fmac_f32_e32 v34, v27, v151
	v_fmac_f32_e32 v38, v27, v163
	v_fmac_f32_e32 v33, v23, v151
	v_fmac_f32_e32 v35, v23, v163
	v_add_f32_dpp v28, v34, v33 row_half_mirror row_mask:0xf bank_mask:0xf
	v_add_f32_dpp v32, v38, v35 row_half_mirror row_mask:0xf bank_mask:0xf
	v_pk_mul_f32 v[20:21], v[20:21], v[172:173]
	v_add_f32_dpp v28, v28, v28 row_ror:8 row_mask:0xf bank_mask:0xf
	v_add_f32_dpp v32, v32, v32 row_ror:8 row_mask:0xf bank_mask:0xf
	v_pk_mul_f32 v[22:23], v[22:23], v[174:175]
	v_add_f32_dpp v28, v28, v28 quad_perm:[1,0,3,2] row_mask:0xf bank_mask:0xf
	v_add_f32_dpp v32, v32, v32 quad_perm:[1,0,3,2] row_mask:0xf bank_mask:0xf
	v_pk_mul_f32 v[24:25], v[24:25], v[172:173]
	v_add_f32_dpp v28, v28, v28 quad_perm:[2,3,0,1] row_mask:0xf bank_mask:0xf
	v_add_f32_dpp v32, v32, v32 quad_perm:[2,3,0,1] row_mask:0xf bank_mask:0xf
	v_pk_mul_f32 v[26:27], v[26:27], v[174:175]
	v_pk_fma_f32 v[20:21], v[184:185], v[12:13], v[20:21] op_sel_hi:[1,0,1]
	v_mov_b32_dpp v30, v28 row_half_mirror row_mask:0xf bank_mask:0xf
	v_pk_fma_f32 v[22:23], v[186:187], v[12:13], v[22:23] op_sel_hi:[1,0,1]
	v_pk_fma_f32 v[24:25], v[184:185], v[14:15], v[24:25] op_sel_hi:[1,0,1]
	v_pk_fma_f32 v[26:27], v[186:187], v[14:15], v[26:27] op_sel_hi:[1,0,1]
	v_pk_fma_f32 v[20:21], v[92:93], v[28:29], v[20:21] op_sel_hi:[1,0,1] neg_lo:[0,1,0] neg_hi:[0,1,0]
	v_pk_fma_f32 v[22:23], v[94:95], v[28:29], v[22:23] op_sel_hi:[1,0,1] neg_lo:[0,1,0] neg_hi:[0,1,0]
	v_pk_fma_f32 v[24:25], v[92:93], v[30:31], v[24:25] op_sel_hi:[1,0,1] neg_lo:[0,1,0] neg_hi:[0,1,0]
	v_pk_fma_f32 v[26:27], v[94:95], v[30:31], v[26:27] op_sel_hi:[1,0,1] neg_lo:[0,1,0] neg_hi:[0,1,0]
	v_add_f32_e32 v39, v32, v13
	ds_write_b32 v102, v39 offset:640
	ds_read_b128 v[148:151], v195 offset:2048
	ds_read_b128 v[160:163], v195 offset:34816
	ds_read_b128 v[172:175], v195 offset:26624
	ds_read_b128 v[184:187], v195 offset:18432
	ds_read_b128 v[92:95], v195 offset:10240
	ds_read_b64 v[12:13], v196 offset:4096
	ds_read_b64 v[14:15], v36 offset:4096
	s_waitcnt lgkmcnt(15)
	v_mul_f32_e32 v34, v24, v140
	v_mul_f32_e32 v38, v24, v152
	v_mul_f32_e32 v33, v20, v140
	v_mul_f32_e32 v35, v20, v152
	v_fmac_f32_e32 v34, v25, v141
	v_fmac_f32_e32 v38, v25, v153
	v_fmac_f32_e32 v33, v21, v141
	v_fmac_f32_e32 v35, v21, v153
	v_fmac_f32_e32 v34, v26, v142
	v_fmac_f32_e32 v38, v26, v154
	v_fmac_f32_e32 v33, v22, v142
	v_fmac_f32_e32 v35, v22, v154
	v_fmac_f32_e32 v34, v27, v143
	v_fmac_f32_e32 v38, v27, v155
	v_fmac_f32_e32 v33, v23, v143
	v_fmac_f32_e32 v35, v23, v155
	v_add_f32_dpp v28, v34, v33 row_half_mirror row_mask:0xf bank_mask:0xf
	v_add_f32_dpp v32, v38, v35 row_half_mirror row_mask:0xf bank_mask:0xf
	v_pk_mul_f32 v[20:21], v[20:21], v[164:165]
	v_add_f32_dpp v28, v28, v28 row_ror:8 row_mask:0xf bank_mask:0xf
	v_add_f32_dpp v32, v32, v32 row_ror:8 row_mask:0xf bank_mask:0xf
	v_pk_mul_f32 v[22:23], v[22:23], v[166:167]
	v_add_f32_dpp v28, v28, v28 quad_perm:[1,0,3,2] row_mask:0xf bank_mask:0xf
	v_add_f32_dpp v32, v32, v32 quad_perm:[1,0,3,2] row_mask:0xf bank_mask:0xf
	v_pk_mul_f32 v[24:25], v[24:25], v[164:165]
	v_add_f32_dpp v28, v28, v28 quad_perm:[2,3,0,1] row_mask:0xf bank_mask:0xf
	v_add_f32_dpp v32, v32, v32 quad_perm:[2,3,0,1] row_mask:0xf bank_mask:0xf
	v_pk_mul_f32 v[26:27], v[26:27], v[166:167]
	v_pk_fma_f32 v[20:21], v[176:177], v[4:5], v[20:21] op_sel_hi:[1,0,1]
	v_mov_b32_dpp v30, v28 row_half_mirror row_mask:0xf bank_mask:0xf
	v_pk_fma_f32 v[22:23], v[178:179], v[4:5], v[22:23] op_sel_hi:[1,0,1]
	v_pk_fma_f32 v[24:25], v[176:177], v[6:7], v[24:25] op_sel_hi:[1,0,1]
	v_pk_fma_f32 v[26:27], v[178:179], v[6:7], v[26:27] op_sel_hi:[1,0,1]
	v_pk_fma_f32 v[20:21], v[84:85], v[28:29], v[20:21] op_sel_hi:[1,0,1] neg_lo:[0,1,0] neg_hi:[0,1,0]
	v_pk_fma_f32 v[22:23], v[86:87], v[28:29], v[22:23] op_sel_hi:[1,0,1] neg_lo:[0,1,0] neg_hi:[0,1,0]
	v_pk_fma_f32 v[24:25], v[84:85], v[30:31], v[24:25] op_sel_hi:[1,0,1] neg_lo:[0,1,0] neg_hi:[0,1,0]
	v_pk_fma_f32 v[26:27], v[86:87], v[30:31], v[26:27] op_sel_hi:[1,0,1] neg_lo:[0,1,0] neg_hi:[0,1,0]
	v_add_f32_e32 v39, v32, v5
	ds_write_b32 v102, v39 offset:768
	ds_read_b128 v[140:143], v195 offset:2304
	ds_read_b128 v[152:155], v195 offset:35072
	ds_read_b128 v[164:167], v195 offset:26880
	ds_read_b128 v[176:179], v195 offset:18688
	ds_read_b128 v[84:87], v195 offset:10496
	ds_read_b64 v[4:5], v196 offset:4608
	ds_read_b64 v[6:7], v36 offset:4608
	s_waitcnt lgkmcnt(15)
	v_mul_f32_e32 v34, v24, v144
	v_mul_f32_e32 v38, v24, v156
	v_mul_f32_e32 v33, v20, v144
	v_mul_f32_e32 v35, v20, v156
	v_fmac_f32_e32 v34, v25, v145
	v_fmac_f32_e32 v38, v25, v157
	v_fmac_f32_e32 v33, v21, v145
	v_fmac_f32_e32 v35, v21, v157
	v_fmac_f32_e32 v34, v26, v146
	v_fmac_f32_e32 v38, v26, v158
	v_fmac_f32_e32 v33, v22, v146
	v_fmac_f32_e32 v35, v22, v158
	v_fmac_f32_e32 v34, v27, v147
	v_fmac_f32_e32 v38, v27, v159
	v_fmac_f32_e32 v33, v23, v147
	v_fmac_f32_e32 v35, v23, v159
	v_add_f32_dpp v28, v34, v33 row_half_mirror row_mask:0xf bank_mask:0xf
	v_add_f32_dpp v32, v38, v35 row_half_mirror row_mask:0xf bank_mask:0xf
	v_pk_mul_f32 v[20:21], v[20:21], v[168:169]
	v_add_f32_dpp v28, v28, v28 row_ror:8 row_mask:0xf bank_mask:0xf
	v_add_f32_dpp v32, v32, v32 row_ror:8 row_mask:0xf bank_mask:0xf
	v_pk_mul_f32 v[22:23], v[22:23], v[170:171]
	v_add_f32_dpp v28, v28, v28 quad_perm:[1,0,3,2] row_mask:0xf bank_mask:0xf
	v_add_f32_dpp v32, v32, v32 quad_perm:[1,0,3,2] row_mask:0xf bank_mask:0xf
	v_pk_mul_f32 v[24:25], v[24:25], v[168:169]
	v_add_f32_dpp v28, v28, v28 quad_perm:[2,3,0,1] row_mask:0xf bank_mask:0xf
	v_add_f32_dpp v32, v32, v32 quad_perm:[2,3,0,1] row_mask:0xf bank_mask:0xf
	v_pk_mul_f32 v[26:27], v[26:27], v[170:171]
	v_pk_fma_f32 v[20:21], v[180:181], v[8:9], v[20:21] op_sel_hi:[1,0,1]
	v_mov_b32_dpp v30, v28 row_half_mirror row_mask:0xf bank_mask:0xf
	v_pk_fma_f32 v[22:23], v[182:183], v[8:9], v[22:23] op_sel_hi:[1,0,1]
	v_pk_fma_f32 v[24:25], v[180:181], v[10:11], v[24:25] op_sel_hi:[1,0,1]
	v_pk_fma_f32 v[26:27], v[182:183], v[10:11], v[26:27] op_sel_hi:[1,0,1]
	v_pk_fma_f32 v[20:21], v[88:89], v[28:29], v[20:21] op_sel_hi:[1,0,1] neg_lo:[0,1,0] neg_hi:[0,1,0]
	v_pk_fma_f32 v[22:23], v[90:91], v[28:29], v[22:23] op_sel_hi:[1,0,1] neg_lo:[0,1,0] neg_hi:[0,1,0]
	v_pk_fma_f32 v[24:25], v[88:89], v[30:31], v[24:25] op_sel_hi:[1,0,1] neg_lo:[0,1,0] neg_hi:[0,1,0]
	v_pk_fma_f32 v[26:27], v[90:91], v[30:31], v[26:27] op_sel_hi:[1,0,1] neg_lo:[0,1,0] neg_hi:[0,1,0]
	v_add_f32_e32 v39, v32, v9
	ds_write_b32 v102, v39 offset:896
	ds_read_b128 v[144:147], v195 offset:2560
	ds_read_b128 v[156:159], v195 offset:35328
	ds_read_b128 v[168:171], v195 offset:27136
	ds_read_b128 v[180:183], v195 offset:18944
	ds_read_b128 v[88:91], v195 offset:10752
	ds_read_b64 v[8:9], v196 offset:5120
	ds_read_b64 v[10:11], v36 offset:5120
	s_waitcnt lgkmcnt(15)
	v_mul_f32_e32 v34, v24, v148
	v_mul_f32_e32 v38, v24, v160
	v_mul_f32_e32 v33, v20, v148
	v_mul_f32_e32 v35, v20, v160
	v_fmac_f32_e32 v34, v25, v149
	v_fmac_f32_e32 v38, v25, v161
	v_fmac_f32_e32 v33, v21, v149
	v_fmac_f32_e32 v35, v21, v161
	v_fmac_f32_e32 v34, v26, v150
	v_fmac_f32_e32 v38, v26, v162
	v_fmac_f32_e32 v33, v22, v150
	v_fmac_f32_e32 v35, v22, v162
	v_fmac_f32_e32 v34, v27, v151
	v_fmac_f32_e32 v38, v27, v163
	v_fmac_f32_e32 v33, v23, v151
	v_fmac_f32_e32 v35, v23, v163
	v_add_f32_dpp v28, v34, v33 row_half_mirror row_mask:0xf bank_mask:0xf
	v_add_f32_dpp v32, v38, v35 row_half_mirror row_mask:0xf bank_mask:0xf
	v_pk_mul_f32 v[20:21], v[20:21], v[172:173]
	v_add_f32_dpp v28, v28, v28 row_ror:8 row_mask:0xf bank_mask:0xf
	v_add_f32_dpp v32, v32, v32 row_ror:8 row_mask:0xf bank_mask:0xf
	v_pk_mul_f32 v[22:23], v[22:23], v[174:175]
	v_add_f32_dpp v28, v28, v28 quad_perm:[1,0,3,2] row_mask:0xf bank_mask:0xf
	v_add_f32_dpp v32, v32, v32 quad_perm:[1,0,3,2] row_mask:0xf bank_mask:0xf
	v_pk_mul_f32 v[24:25], v[24:25], v[172:173]
	v_add_f32_dpp v28, v28, v28 quad_perm:[2,3,0,1] row_mask:0xf bank_mask:0xf
	v_add_f32_dpp v32, v32, v32 quad_perm:[2,3,0,1] row_mask:0xf bank_mask:0xf
	v_pk_mul_f32 v[26:27], v[26:27], v[174:175]
	v_pk_fma_f32 v[20:21], v[184:185], v[12:13], v[20:21] op_sel_hi:[1,0,1]
	v_mov_b32_dpp v30, v28 row_half_mirror row_mask:0xf bank_mask:0xf
	v_pk_fma_f32 v[22:23], v[186:187], v[12:13], v[22:23] op_sel_hi:[1,0,1]
	v_pk_fma_f32 v[24:25], v[184:185], v[14:15], v[24:25] op_sel_hi:[1,0,1]
	v_pk_fma_f32 v[26:27], v[186:187], v[14:15], v[26:27] op_sel_hi:[1,0,1]
	v_pk_fma_f32 v[20:21], v[92:93], v[28:29], v[20:21] op_sel_hi:[1,0,1] neg_lo:[0,1,0] neg_hi:[0,1,0]
	v_pk_fma_f32 v[22:23], v[94:95], v[28:29], v[22:23] op_sel_hi:[1,0,1] neg_lo:[0,1,0] neg_hi:[0,1,0]
	v_pk_fma_f32 v[24:25], v[92:93], v[30:31], v[24:25] op_sel_hi:[1,0,1] neg_lo:[0,1,0] neg_hi:[0,1,0]
	v_pk_fma_f32 v[26:27], v[94:95], v[30:31], v[26:27] op_sel_hi:[1,0,1] neg_lo:[0,1,0] neg_hi:[0,1,0]
	v_add_f32_e32 v39, v32, v13
	ds_write_b32 v102, v39 offset:1024
	ds_read_b128 v[148:151], v195 offset:2816
	ds_read_b128 v[160:163], v195 offset:35584
	ds_read_b128 v[172:175], v195 offset:27392
	ds_read_b128 v[184:187], v195 offset:19200
	ds_read_b128 v[92:95], v195 offset:11008
	ds_read_b64 v[12:13], v196 offset:5632
	ds_read_b64 v[14:15], v36 offset:5632
	s_waitcnt lgkmcnt(15)
	v_mul_f32_e32 v34, v24, v140
	v_mul_f32_e32 v38, v24, v152
	v_mul_f32_e32 v33, v20, v140
	v_mul_f32_e32 v35, v20, v152
	v_fmac_f32_e32 v34, v25, v141
	v_fmac_f32_e32 v38, v25, v153
	v_fmac_f32_e32 v33, v21, v141
	v_fmac_f32_e32 v35, v21, v153
	v_fmac_f32_e32 v34, v26, v142
	v_fmac_f32_e32 v38, v26, v154
	v_fmac_f32_e32 v33, v22, v142
	v_fmac_f32_e32 v35, v22, v154
	v_fmac_f32_e32 v34, v27, v143
	v_fmac_f32_e32 v38, v27, v155
	v_fmac_f32_e32 v33, v23, v143
	v_fmac_f32_e32 v35, v23, v155
	v_add_f32_dpp v28, v34, v33 row_half_mirror row_mask:0xf bank_mask:0xf
	v_add_f32_dpp v32, v38, v35 row_half_mirror row_mask:0xf bank_mask:0xf
	v_pk_mul_f32 v[20:21], v[20:21], v[164:165]
	v_add_f32_dpp v28, v28, v28 row_ror:8 row_mask:0xf bank_mask:0xf
	v_add_f32_dpp v32, v32, v32 row_ror:8 row_mask:0xf bank_mask:0xf
	v_pk_mul_f32 v[22:23], v[22:23], v[166:167]
	v_add_f32_dpp v28, v28, v28 quad_perm:[1,0,3,2] row_mask:0xf bank_mask:0xf
	v_add_f32_dpp v32, v32, v32 quad_perm:[1,0,3,2] row_mask:0xf bank_mask:0xf
	v_pk_mul_f32 v[24:25], v[24:25], v[164:165]
	v_add_f32_dpp v28, v28, v28 quad_perm:[2,3,0,1] row_mask:0xf bank_mask:0xf
	v_add_f32_dpp v32, v32, v32 quad_perm:[2,3,0,1] row_mask:0xf bank_mask:0xf
	v_pk_mul_f32 v[26:27], v[26:27], v[166:167]
	v_pk_fma_f32 v[20:21], v[176:177], v[4:5], v[20:21] op_sel_hi:[1,0,1]
	v_mov_b32_dpp v30, v28 row_half_mirror row_mask:0xf bank_mask:0xf
	v_pk_fma_f32 v[22:23], v[178:179], v[4:5], v[22:23] op_sel_hi:[1,0,1]
	v_pk_fma_f32 v[24:25], v[176:177], v[6:7], v[24:25] op_sel_hi:[1,0,1]
	v_pk_fma_f32 v[26:27], v[178:179], v[6:7], v[26:27] op_sel_hi:[1,0,1]
	v_pk_fma_f32 v[20:21], v[84:85], v[28:29], v[20:21] op_sel_hi:[1,0,1] neg_lo:[0,1,0] neg_hi:[0,1,0]
	v_pk_fma_f32 v[22:23], v[86:87], v[28:29], v[22:23] op_sel_hi:[1,0,1] neg_lo:[0,1,0] neg_hi:[0,1,0]
	v_pk_fma_f32 v[24:25], v[84:85], v[30:31], v[24:25] op_sel_hi:[1,0,1] neg_lo:[0,1,0] neg_hi:[0,1,0]
	v_pk_fma_f32 v[26:27], v[86:87], v[30:31], v[26:27] op_sel_hi:[1,0,1] neg_lo:[0,1,0] neg_hi:[0,1,0]
	v_add_f32_e32 v39, v32, v5
	ds_write_b32 v102, v39 offset:1152
	ds_read_b128 v[140:143], v195 offset:3072
	ds_read_b128 v[152:155], v195 offset:35840
	ds_read_b128 v[164:167], v195 offset:27648
	ds_read_b128 v[176:179], v195 offset:19456
	ds_read_b128 v[84:87], v195 offset:11264
	ds_read_b64 v[4:5], v196 offset:6144
	ds_read_b64 v[6:7], v36 offset:6144
	s_waitcnt lgkmcnt(15)
	v_mul_f32_e32 v34, v24, v144
	v_mul_f32_e32 v38, v24, v156
	v_mul_f32_e32 v33, v20, v144
	v_mul_f32_e32 v35, v20, v156
	v_fmac_f32_e32 v34, v25, v145
	v_fmac_f32_e32 v38, v25, v157
	v_fmac_f32_e32 v33, v21, v145
	v_fmac_f32_e32 v35, v21, v157
	v_fmac_f32_e32 v34, v26, v146
	v_fmac_f32_e32 v38, v26, v158
	v_fmac_f32_e32 v33, v22, v146
	v_fmac_f32_e32 v35, v22, v158
	v_fmac_f32_e32 v34, v27, v147
	v_fmac_f32_e32 v38, v27, v159
	v_fmac_f32_e32 v33, v23, v147
	v_fmac_f32_e32 v35, v23, v159
	v_add_f32_dpp v28, v34, v33 row_half_mirror row_mask:0xf bank_mask:0xf
	v_add_f32_dpp v32, v38, v35 row_half_mirror row_mask:0xf bank_mask:0xf
	v_pk_mul_f32 v[20:21], v[20:21], v[168:169]
	v_add_f32_dpp v28, v28, v28 row_ror:8 row_mask:0xf bank_mask:0xf
	v_add_f32_dpp v32, v32, v32 row_ror:8 row_mask:0xf bank_mask:0xf
	v_pk_mul_f32 v[22:23], v[22:23], v[170:171]
	v_add_f32_dpp v28, v28, v28 quad_perm:[1,0,3,2] row_mask:0xf bank_mask:0xf
	v_add_f32_dpp v32, v32, v32 quad_perm:[1,0,3,2] row_mask:0xf bank_mask:0xf
	v_pk_mul_f32 v[24:25], v[24:25], v[168:169]
	v_add_f32_dpp v28, v28, v28 quad_perm:[2,3,0,1] row_mask:0xf bank_mask:0xf
	v_add_f32_dpp v32, v32, v32 quad_perm:[2,3,0,1] row_mask:0xf bank_mask:0xf
	v_pk_mul_f32 v[26:27], v[26:27], v[170:171]
	v_pk_fma_f32 v[20:21], v[180:181], v[8:9], v[20:21] op_sel_hi:[1,0,1]
	v_mov_b32_dpp v30, v28 row_half_mirror row_mask:0xf bank_mask:0xf
	v_pk_fma_f32 v[22:23], v[182:183], v[8:9], v[22:23] op_sel_hi:[1,0,1]
	v_pk_fma_f32 v[24:25], v[180:181], v[10:11], v[24:25] op_sel_hi:[1,0,1]
	v_pk_fma_f32 v[26:27], v[182:183], v[10:11], v[26:27] op_sel_hi:[1,0,1]
	v_pk_fma_f32 v[20:21], v[88:89], v[28:29], v[20:21] op_sel_hi:[1,0,1] neg_lo:[0,1,0] neg_hi:[0,1,0]
	v_pk_fma_f32 v[22:23], v[90:91], v[28:29], v[22:23] op_sel_hi:[1,0,1] neg_lo:[0,1,0] neg_hi:[0,1,0]
	v_pk_fma_f32 v[24:25], v[88:89], v[30:31], v[24:25] op_sel_hi:[1,0,1] neg_lo:[0,1,0] neg_hi:[0,1,0]
	v_pk_fma_f32 v[26:27], v[90:91], v[30:31], v[26:27] op_sel_hi:[1,0,1] neg_lo:[0,1,0] neg_hi:[0,1,0]
	v_add_f32_e32 v39, v32, v9
	ds_write_b32 v102, v39 offset:1280
	ds_read_b128 v[144:147], v195 offset:3328
	ds_read_b128 v[156:159], v195 offset:36096
	ds_read_b128 v[168:171], v195 offset:27904
	ds_read_b128 v[180:183], v195 offset:19712
	ds_read_b128 v[88:91], v195 offset:11520
	ds_read_b64 v[8:9], v196 offset:6656
	ds_read_b64 v[10:11], v36 offset:6656
	s_waitcnt lgkmcnt(15)
	v_mul_f32_e32 v34, v24, v148
	v_mul_f32_e32 v38, v24, v160
	v_mul_f32_e32 v33, v20, v148
	v_mul_f32_e32 v35, v20, v160
	v_fmac_f32_e32 v34, v25, v149
	v_fmac_f32_e32 v38, v25, v161
	v_fmac_f32_e32 v33, v21, v149
	v_fmac_f32_e32 v35, v21, v161
	v_fmac_f32_e32 v34, v26, v150
	v_fmac_f32_e32 v38, v26, v162
	v_fmac_f32_e32 v33, v22, v150
	v_fmac_f32_e32 v35, v22, v162
	v_fmac_f32_e32 v34, v27, v151
	v_fmac_f32_e32 v38, v27, v163
	v_fmac_f32_e32 v33, v23, v151
	v_fmac_f32_e32 v35, v23, v163
	v_add_f32_dpp v28, v34, v33 row_half_mirror row_mask:0xf bank_mask:0xf
	v_add_f32_dpp v32, v38, v35 row_half_mirror row_mask:0xf bank_mask:0xf
	v_pk_mul_f32 v[20:21], v[20:21], v[172:173]
	v_add_f32_dpp v28, v28, v28 row_ror:8 row_mask:0xf bank_mask:0xf
	v_add_f32_dpp v32, v32, v32 row_ror:8 row_mask:0xf bank_mask:0xf
	v_pk_mul_f32 v[22:23], v[22:23], v[174:175]
	v_add_f32_dpp v28, v28, v28 quad_perm:[1,0,3,2] row_mask:0xf bank_mask:0xf
	v_add_f32_dpp v32, v32, v32 quad_perm:[1,0,3,2] row_mask:0xf bank_mask:0xf
	v_pk_mul_f32 v[24:25], v[24:25], v[172:173]
	v_add_f32_dpp v28, v28, v28 quad_perm:[2,3,0,1] row_mask:0xf bank_mask:0xf
	v_add_f32_dpp v32, v32, v32 quad_perm:[2,3,0,1] row_mask:0xf bank_mask:0xf
	v_pk_mul_f32 v[26:27], v[26:27], v[174:175]
	v_pk_fma_f32 v[20:21], v[184:185], v[12:13], v[20:21] op_sel_hi:[1,0,1]
	v_mov_b32_dpp v30, v28 row_half_mirror row_mask:0xf bank_mask:0xf
	v_pk_fma_f32 v[22:23], v[186:187], v[12:13], v[22:23] op_sel_hi:[1,0,1]
	v_pk_fma_f32 v[24:25], v[184:185], v[14:15], v[24:25] op_sel_hi:[1,0,1]
	v_pk_fma_f32 v[26:27], v[186:187], v[14:15], v[26:27] op_sel_hi:[1,0,1]
	v_pk_fma_f32 v[20:21], v[92:93], v[28:29], v[20:21] op_sel_hi:[1,0,1] neg_lo:[0,1,0] neg_hi:[0,1,0]
	v_pk_fma_f32 v[22:23], v[94:95], v[28:29], v[22:23] op_sel_hi:[1,0,1] neg_lo:[0,1,0] neg_hi:[0,1,0]
	v_pk_fma_f32 v[24:25], v[92:93], v[30:31], v[24:25] op_sel_hi:[1,0,1] neg_lo:[0,1,0] neg_hi:[0,1,0]
	v_pk_fma_f32 v[26:27], v[94:95], v[30:31], v[26:27] op_sel_hi:[1,0,1] neg_lo:[0,1,0] neg_hi:[0,1,0]
	v_add_f32_e32 v39, v32, v13
	ds_write_b32 v102, v39 offset:1408
	ds_read_b128 v[148:151], v195 offset:3584
	ds_read_b128 v[160:163], v195 offset:36352
	ds_read_b128 v[172:175], v195 offset:28160
	ds_read_b128 v[184:187], v195 offset:19968
	ds_read_b128 v[92:95], v195 offset:11776
	ds_read_b64 v[12:13], v196 offset:7168
	ds_read_b64 v[14:15], v36 offset:7168
	s_waitcnt lgkmcnt(15)
	v_mul_f32_e32 v34, v24, v140
	v_mul_f32_e32 v38, v24, v152
	v_mul_f32_e32 v33, v20, v140
	v_mul_f32_e32 v35, v20, v152
	v_fmac_f32_e32 v34, v25, v141
	v_fmac_f32_e32 v38, v25, v153
	v_fmac_f32_e32 v33, v21, v141
	v_fmac_f32_e32 v35, v21, v153
	v_fmac_f32_e32 v34, v26, v142
	v_fmac_f32_e32 v38, v26, v154
	v_fmac_f32_e32 v33, v22, v142
	v_fmac_f32_e32 v35, v22, v154
	v_fmac_f32_e32 v34, v27, v143
	v_fmac_f32_e32 v38, v27, v155
	v_fmac_f32_e32 v33, v23, v143
	v_fmac_f32_e32 v35, v23, v155
	v_add_f32_dpp v28, v34, v33 row_half_mirror row_mask:0xf bank_mask:0xf
	v_add_f32_dpp v32, v38, v35 row_half_mirror row_mask:0xf bank_mask:0xf
	v_pk_mul_f32 v[20:21], v[20:21], v[164:165]
	v_add_f32_dpp v28, v28, v28 row_ror:8 row_mask:0xf bank_mask:0xf
	v_add_f32_dpp v32, v32, v32 row_ror:8 row_mask:0xf bank_mask:0xf
	v_pk_mul_f32 v[22:23], v[22:23], v[166:167]
	v_add_f32_dpp v28, v28, v28 quad_perm:[1,0,3,2] row_mask:0xf bank_mask:0xf
	v_add_f32_dpp v32, v32, v32 quad_perm:[1,0,3,2] row_mask:0xf bank_mask:0xf
	v_pk_mul_f32 v[24:25], v[24:25], v[164:165]
	v_add_f32_dpp v28, v28, v28 quad_perm:[2,3,0,1] row_mask:0xf bank_mask:0xf
	v_add_f32_dpp v32, v32, v32 quad_perm:[2,3,0,1] row_mask:0xf bank_mask:0xf
	v_pk_mul_f32 v[26:27], v[26:27], v[166:167]
	v_pk_fma_f32 v[20:21], v[176:177], v[4:5], v[20:21] op_sel_hi:[1,0,1]
	v_mov_b32_dpp v30, v28 row_half_mirror row_mask:0xf bank_mask:0xf
	v_pk_fma_f32 v[22:23], v[178:179], v[4:5], v[22:23] op_sel_hi:[1,0,1]
	v_pk_fma_f32 v[24:25], v[176:177], v[6:7], v[24:25] op_sel_hi:[1,0,1]
	v_pk_fma_f32 v[26:27], v[178:179], v[6:7], v[26:27] op_sel_hi:[1,0,1]
	v_pk_fma_f32 v[20:21], v[84:85], v[28:29], v[20:21] op_sel_hi:[1,0,1] neg_lo:[0,1,0] neg_hi:[0,1,0]
	v_pk_fma_f32 v[22:23], v[86:87], v[28:29], v[22:23] op_sel_hi:[1,0,1] neg_lo:[0,1,0] neg_hi:[0,1,0]
	v_pk_fma_f32 v[24:25], v[84:85], v[30:31], v[24:25] op_sel_hi:[1,0,1] neg_lo:[0,1,0] neg_hi:[0,1,0]
	v_pk_fma_f32 v[26:27], v[86:87], v[30:31], v[26:27] op_sel_hi:[1,0,1] neg_lo:[0,1,0] neg_hi:[0,1,0]
	v_add_f32_e32 v39, v32, v5
	ds_write_b32 v102, v39 offset:1536
	ds_read_b128 v[140:143], v195 offset:3840
	ds_read_b128 v[152:155], v195 offset:36608
	ds_read_b128 v[164:167], v195 offset:28416
	ds_read_b128 v[176:179], v195 offset:20224
	ds_read_b128 v[84:87], v195 offset:12032
	ds_read_b64 v[4:5], v196 offset:7680
	ds_read_b64 v[6:7], v36 offset:7680
	s_waitcnt lgkmcnt(15)
	v_mul_f32_e32 v34, v24, v144
	v_mul_f32_e32 v38, v24, v156
	v_mul_f32_e32 v33, v20, v144
	v_mul_f32_e32 v35, v20, v156
	v_fmac_f32_e32 v34, v25, v145
	v_fmac_f32_e32 v38, v25, v157
	v_fmac_f32_e32 v33, v21, v145
	v_fmac_f32_e32 v35, v21, v157
	v_fmac_f32_e32 v34, v26, v146
	v_fmac_f32_e32 v38, v26, v158
	v_fmac_f32_e32 v33, v22, v146
	v_fmac_f32_e32 v35, v22, v158
	v_fmac_f32_e32 v34, v27, v147
	v_fmac_f32_e32 v38, v27, v159
	v_fmac_f32_e32 v33, v23, v147
	v_fmac_f32_e32 v35, v23, v159
	v_add_f32_dpp v28, v34, v33 row_half_mirror row_mask:0xf bank_mask:0xf
	v_add_f32_dpp v32, v38, v35 row_half_mirror row_mask:0xf bank_mask:0xf
	v_pk_mul_f32 v[20:21], v[20:21], v[168:169]
	v_add_f32_dpp v28, v28, v28 row_ror:8 row_mask:0xf bank_mask:0xf
	v_add_f32_dpp v32, v32, v32 row_ror:8 row_mask:0xf bank_mask:0xf
	v_pk_mul_f32 v[22:23], v[22:23], v[170:171]
	v_add_f32_dpp v28, v28, v28 quad_perm:[1,0,3,2] row_mask:0xf bank_mask:0xf
	v_add_f32_dpp v32, v32, v32 quad_perm:[1,0,3,2] row_mask:0xf bank_mask:0xf
	v_pk_mul_f32 v[24:25], v[24:25], v[168:169]
	v_add_f32_dpp v28, v28, v28 quad_perm:[2,3,0,1] row_mask:0xf bank_mask:0xf
	v_add_f32_dpp v32, v32, v32 quad_perm:[2,3,0,1] row_mask:0xf bank_mask:0xf
	v_pk_mul_f32 v[26:27], v[26:27], v[170:171]
	v_pk_fma_f32 v[20:21], v[180:181], v[8:9], v[20:21] op_sel_hi:[1,0,1]
	v_mov_b32_dpp v30, v28 row_half_mirror row_mask:0xf bank_mask:0xf
	v_pk_fma_f32 v[22:23], v[182:183], v[8:9], v[22:23] op_sel_hi:[1,0,1]
	v_pk_fma_f32 v[24:25], v[180:181], v[10:11], v[24:25] op_sel_hi:[1,0,1]
	v_pk_fma_f32 v[26:27], v[182:183], v[10:11], v[26:27] op_sel_hi:[1,0,1]
	v_pk_fma_f32 v[20:21], v[88:89], v[28:29], v[20:21] op_sel_hi:[1,0,1] neg_lo:[0,1,0] neg_hi:[0,1,0]
	v_pk_fma_f32 v[22:23], v[90:91], v[28:29], v[22:23] op_sel_hi:[1,0,1] neg_lo:[0,1,0] neg_hi:[0,1,0]
	v_pk_fma_f32 v[24:25], v[88:89], v[30:31], v[24:25] op_sel_hi:[1,0,1] neg_lo:[0,1,0] neg_hi:[0,1,0]
	v_pk_fma_f32 v[26:27], v[90:91], v[30:31], v[26:27] op_sel_hi:[1,0,1] neg_lo:[0,1,0] neg_hi:[0,1,0]
	v_add_f32_e32 v39, v32, v9
	ds_write_b32 v102, v39 offset:1664
	ds_read_b128 v[144:147], v195 offset:4096
	ds_read_b128 v[156:159], v195 offset:36864
	ds_read_b128 v[168:171], v195 offset:28672
	ds_read_b128 v[180:183], v195 offset:20480
	ds_read_b128 v[88:91], v195 offset:12288
	ds_read_b64 v[8:9], v196 offset:8192
	ds_read_b64 v[10:11], v36 offset:8192
	s_waitcnt lgkmcnt(15)
	v_mul_f32_e32 v34, v24, v148
	v_mul_f32_e32 v38, v24, v160
	v_mul_f32_e32 v33, v20, v148
	v_mul_f32_e32 v35, v20, v160
	v_fmac_f32_e32 v34, v25, v149
	v_fmac_f32_e32 v38, v25, v161
	v_fmac_f32_e32 v33, v21, v149
	v_fmac_f32_e32 v35, v21, v161
	v_fmac_f32_e32 v34, v26, v150
	v_fmac_f32_e32 v38, v26, v162
	v_fmac_f32_e32 v33, v22, v150
	v_fmac_f32_e32 v35, v22, v162
	v_fmac_f32_e32 v34, v27, v151
	v_fmac_f32_e32 v38, v27, v163
	v_fmac_f32_e32 v33, v23, v151
	v_fmac_f32_e32 v35, v23, v163
	v_add_f32_dpp v28, v34, v33 row_half_mirror row_mask:0xf bank_mask:0xf
	v_add_f32_dpp v32, v38, v35 row_half_mirror row_mask:0xf bank_mask:0xf
	v_pk_mul_f32 v[20:21], v[20:21], v[172:173]
	v_add_f32_dpp v28, v28, v28 row_ror:8 row_mask:0xf bank_mask:0xf
	v_add_f32_dpp v32, v32, v32 row_ror:8 row_mask:0xf bank_mask:0xf
	v_pk_mul_f32 v[22:23], v[22:23], v[174:175]
	v_add_f32_dpp v28, v28, v28 quad_perm:[1,0,3,2] row_mask:0xf bank_mask:0xf
	v_add_f32_dpp v32, v32, v32 quad_perm:[1,0,3,2] row_mask:0xf bank_mask:0xf
	v_pk_mul_f32 v[24:25], v[24:25], v[172:173]
	v_add_f32_dpp v28, v28, v28 quad_perm:[2,3,0,1] row_mask:0xf bank_mask:0xf
	v_add_f32_dpp v32, v32, v32 quad_perm:[2,3,0,1] row_mask:0xf bank_mask:0xf
	v_pk_mul_f32 v[26:27], v[26:27], v[174:175]
	v_pk_fma_f32 v[20:21], v[184:185], v[12:13], v[20:21] op_sel_hi:[1,0,1]
	v_mov_b32_dpp v30, v28 row_half_mirror row_mask:0xf bank_mask:0xf
	v_pk_fma_f32 v[22:23], v[186:187], v[12:13], v[22:23] op_sel_hi:[1,0,1]
	v_pk_fma_f32 v[24:25], v[184:185], v[14:15], v[24:25] op_sel_hi:[1,0,1]
	v_pk_fma_f32 v[26:27], v[186:187], v[14:15], v[26:27] op_sel_hi:[1,0,1]
	v_pk_fma_f32 v[20:21], v[92:93], v[28:29], v[20:21] op_sel_hi:[1,0,1] neg_lo:[0,1,0] neg_hi:[0,1,0]
	v_pk_fma_f32 v[22:23], v[94:95], v[28:29], v[22:23] op_sel_hi:[1,0,1] neg_lo:[0,1,0] neg_hi:[0,1,0]
	v_pk_fma_f32 v[24:25], v[92:93], v[30:31], v[24:25] op_sel_hi:[1,0,1] neg_lo:[0,1,0] neg_hi:[0,1,0]
	v_pk_fma_f32 v[26:27], v[94:95], v[30:31], v[26:27] op_sel_hi:[1,0,1] neg_lo:[0,1,0] neg_hi:[0,1,0]
	v_add_f32_e32 v39, v32, v13
	ds_write_b32 v102, v39 offset:1792
	ds_read_b128 v[148:151], v195 offset:4352
	ds_read_b128 v[160:163], v195 offset:37120
	ds_read_b128 v[172:175], v195 offset:28928
	ds_read_b128 v[184:187], v195 offset:20736
	ds_read_b128 v[92:95], v195 offset:12544
	ds_read_b64 v[12:13], v196 offset:8704
	ds_read_b64 v[14:15], v36 offset:8704
	s_waitcnt lgkmcnt(15)
	v_mul_f32_e32 v34, v24, v140
	v_mul_f32_e32 v38, v24, v152
	v_mul_f32_e32 v33, v20, v140
	v_mul_f32_e32 v35, v20, v152
	v_fmac_f32_e32 v34, v25, v141
	v_fmac_f32_e32 v38, v25, v153
	v_fmac_f32_e32 v33, v21, v141
	v_fmac_f32_e32 v35, v21, v153
	v_fmac_f32_e32 v34, v26, v142
	v_fmac_f32_e32 v38, v26, v154
	v_fmac_f32_e32 v33, v22, v142
	v_fmac_f32_e32 v35, v22, v154
	v_fmac_f32_e32 v34, v27, v143
	v_fmac_f32_e32 v38, v27, v155
	v_fmac_f32_e32 v33, v23, v143
	v_fmac_f32_e32 v35, v23, v155
	v_add_f32_dpp v28, v34, v33 row_half_mirror row_mask:0xf bank_mask:0xf
	v_add_f32_dpp v32, v38, v35 row_half_mirror row_mask:0xf bank_mask:0xf
	v_pk_mul_f32 v[20:21], v[20:21], v[164:165]
	v_add_f32_dpp v28, v28, v28 row_ror:8 row_mask:0xf bank_mask:0xf
	v_add_f32_dpp v32, v32, v32 row_ror:8 row_mask:0xf bank_mask:0xf
	v_pk_mul_f32 v[22:23], v[22:23], v[166:167]
	v_add_f32_dpp v28, v28, v28 quad_perm:[1,0,3,2] row_mask:0xf bank_mask:0xf
	v_add_f32_dpp v32, v32, v32 quad_perm:[1,0,3,2] row_mask:0xf bank_mask:0xf
	v_pk_mul_f32 v[24:25], v[24:25], v[164:165]
	v_add_f32_dpp v28, v28, v28 quad_perm:[2,3,0,1] row_mask:0xf bank_mask:0xf
	v_add_f32_dpp v32, v32, v32 quad_perm:[2,3,0,1] row_mask:0xf bank_mask:0xf
	v_pk_mul_f32 v[26:27], v[26:27], v[166:167]
	v_pk_fma_f32 v[20:21], v[176:177], v[4:5], v[20:21] op_sel_hi:[1,0,1]
	v_mov_b32_dpp v30, v28 row_half_mirror row_mask:0xf bank_mask:0xf
	v_pk_fma_f32 v[22:23], v[178:179], v[4:5], v[22:23] op_sel_hi:[1,0,1]
	v_pk_fma_f32 v[24:25], v[176:177], v[6:7], v[24:25] op_sel_hi:[1,0,1]
	v_pk_fma_f32 v[26:27], v[178:179], v[6:7], v[26:27] op_sel_hi:[1,0,1]
	v_pk_fma_f32 v[20:21], v[84:85], v[28:29], v[20:21] op_sel_hi:[1,0,1] neg_lo:[0,1,0] neg_hi:[0,1,0]
	v_pk_fma_f32 v[22:23], v[86:87], v[28:29], v[22:23] op_sel_hi:[1,0,1] neg_lo:[0,1,0] neg_hi:[0,1,0]
	v_pk_fma_f32 v[24:25], v[84:85], v[30:31], v[24:25] op_sel_hi:[1,0,1] neg_lo:[0,1,0] neg_hi:[0,1,0]
	v_pk_fma_f32 v[26:27], v[86:87], v[30:31], v[26:27] op_sel_hi:[1,0,1] neg_lo:[0,1,0] neg_hi:[0,1,0]
	v_add_f32_e32 v39, v32, v5
	ds_write_b32 v102, v39 offset:1920
	ds_read_b128 v[140:143], v195 offset:4608
	ds_read_b128 v[152:155], v195 offset:37376
	ds_read_b128 v[164:167], v195 offset:29184
	ds_read_b128 v[176:179], v195 offset:20992
	ds_read_b128 v[84:87], v195 offset:12800
	ds_read_b64 v[4:5], v196 offset:9216
	ds_read_b64 v[6:7], v36 offset:9216
	s_waitcnt lgkmcnt(15)
	v_mul_f32_e32 v34, v24, v144
	v_mul_f32_e32 v38, v24, v156
	v_mul_f32_e32 v33, v20, v144
	v_mul_f32_e32 v35, v20, v156
	v_fmac_f32_e32 v34, v25, v145
	v_fmac_f32_e32 v38, v25, v157
	v_fmac_f32_e32 v33, v21, v145
	v_fmac_f32_e32 v35, v21, v157
	v_fmac_f32_e32 v34, v26, v146
	v_fmac_f32_e32 v38, v26, v158
	v_fmac_f32_e32 v33, v22, v146
	v_fmac_f32_e32 v35, v22, v158
	v_fmac_f32_e32 v34, v27, v147
	v_fmac_f32_e32 v38, v27, v159
	v_fmac_f32_e32 v33, v23, v147
	v_fmac_f32_e32 v35, v23, v159
	v_add_f32_dpp v28, v34, v33 row_half_mirror row_mask:0xf bank_mask:0xf
	v_add_f32_dpp v32, v38, v35 row_half_mirror row_mask:0xf bank_mask:0xf
	v_pk_mul_f32 v[20:21], v[20:21], v[168:169]
	v_add_f32_dpp v28, v28, v28 row_ror:8 row_mask:0xf bank_mask:0xf
	v_add_f32_dpp v32, v32, v32 row_ror:8 row_mask:0xf bank_mask:0xf
	v_pk_mul_f32 v[22:23], v[22:23], v[170:171]
	v_add_f32_dpp v28, v28, v28 quad_perm:[1,0,3,2] row_mask:0xf bank_mask:0xf
	v_add_f32_dpp v32, v32, v32 quad_perm:[1,0,3,2] row_mask:0xf bank_mask:0xf
	v_pk_mul_f32 v[24:25], v[24:25], v[168:169]
	v_add_f32_dpp v28, v28, v28 quad_perm:[2,3,0,1] row_mask:0xf bank_mask:0xf
	v_add_f32_dpp v32, v32, v32 quad_perm:[2,3,0,1] row_mask:0xf bank_mask:0xf
	v_pk_mul_f32 v[26:27], v[26:27], v[170:171]
	v_pk_fma_f32 v[20:21], v[180:181], v[8:9], v[20:21] op_sel_hi:[1,0,1]
	v_mov_b32_dpp v30, v28 row_half_mirror row_mask:0xf bank_mask:0xf
	v_pk_fma_f32 v[22:23], v[182:183], v[8:9], v[22:23] op_sel_hi:[1,0,1]
	v_pk_fma_f32 v[24:25], v[180:181], v[10:11], v[24:25] op_sel_hi:[1,0,1]
	v_pk_fma_f32 v[26:27], v[182:183], v[10:11], v[26:27] op_sel_hi:[1,0,1]
	v_pk_fma_f32 v[20:21], v[88:89], v[28:29], v[20:21] op_sel_hi:[1,0,1] neg_lo:[0,1,0] neg_hi:[0,1,0]
	v_pk_fma_f32 v[22:23], v[90:91], v[28:29], v[22:23] op_sel_hi:[1,0,1] neg_lo:[0,1,0] neg_hi:[0,1,0]
	v_pk_fma_f32 v[24:25], v[88:89], v[30:31], v[24:25] op_sel_hi:[1,0,1] neg_lo:[0,1,0] neg_hi:[0,1,0]
	v_pk_fma_f32 v[26:27], v[90:91], v[30:31], v[26:27] op_sel_hi:[1,0,1] neg_lo:[0,1,0] neg_hi:[0,1,0]
	v_add_f32_e32 v39, v32, v9
	ds_write_b32 v102, v39 offset:2048
	ds_read_b128 v[144:147], v195 offset:4864
	ds_read_b128 v[156:159], v195 offset:37632
	ds_read_b128 v[168:171], v195 offset:29440
	ds_read_b128 v[180:183], v195 offset:21248
	ds_read_b128 v[88:91], v195 offset:13056
	ds_read_b64 v[8:9], v196 offset:9728
	ds_read_b64 v[10:11], v36 offset:9728
	s_waitcnt lgkmcnt(15)
	v_mul_f32_e32 v34, v24, v148
	v_mul_f32_e32 v38, v24, v160
	v_mul_f32_e32 v33, v20, v148
	v_mul_f32_e32 v35, v20, v160
	v_fmac_f32_e32 v34, v25, v149
	v_fmac_f32_e32 v38, v25, v161
	v_fmac_f32_e32 v33, v21, v149
	v_fmac_f32_e32 v35, v21, v161
	v_fmac_f32_e32 v34, v26, v150
	v_fmac_f32_e32 v38, v26, v162
	v_fmac_f32_e32 v33, v22, v150
	v_fmac_f32_e32 v35, v22, v162
	v_fmac_f32_e32 v34, v27, v151
	v_fmac_f32_e32 v38, v27, v163
	v_fmac_f32_e32 v33, v23, v151
	v_fmac_f32_e32 v35, v23, v163
	v_add_f32_dpp v28, v34, v33 row_half_mirror row_mask:0xf bank_mask:0xf
	v_add_f32_dpp v32, v38, v35 row_half_mirror row_mask:0xf bank_mask:0xf
	v_pk_mul_f32 v[20:21], v[20:21], v[172:173]
	v_add_f32_dpp v28, v28, v28 row_ror:8 row_mask:0xf bank_mask:0xf
	v_add_f32_dpp v32, v32, v32 row_ror:8 row_mask:0xf bank_mask:0xf
	v_pk_mul_f32 v[22:23], v[22:23], v[174:175]
	v_add_f32_dpp v28, v28, v28 quad_perm:[1,0,3,2] row_mask:0xf bank_mask:0xf
	v_add_f32_dpp v32, v32, v32 quad_perm:[1,0,3,2] row_mask:0xf bank_mask:0xf
	v_pk_mul_f32 v[24:25], v[24:25], v[172:173]
	v_add_f32_dpp v28, v28, v28 quad_perm:[2,3,0,1] row_mask:0xf bank_mask:0xf
	v_add_f32_dpp v32, v32, v32 quad_perm:[2,3,0,1] row_mask:0xf bank_mask:0xf
	v_pk_mul_f32 v[26:27], v[26:27], v[174:175]
	v_pk_fma_f32 v[20:21], v[184:185], v[12:13], v[20:21] op_sel_hi:[1,0,1]
	v_mov_b32_dpp v30, v28 row_half_mirror row_mask:0xf bank_mask:0xf
	v_pk_fma_f32 v[22:23], v[186:187], v[12:13], v[22:23] op_sel_hi:[1,0,1]
	v_pk_fma_f32 v[24:25], v[184:185], v[14:15], v[24:25] op_sel_hi:[1,0,1]
	v_pk_fma_f32 v[26:27], v[186:187], v[14:15], v[26:27] op_sel_hi:[1,0,1]
	v_pk_fma_f32 v[20:21], v[92:93], v[28:29], v[20:21] op_sel_hi:[1,0,1] neg_lo:[0,1,0] neg_hi:[0,1,0]
	v_pk_fma_f32 v[22:23], v[94:95], v[28:29], v[22:23] op_sel_hi:[1,0,1] neg_lo:[0,1,0] neg_hi:[0,1,0]
	v_pk_fma_f32 v[24:25], v[92:93], v[30:31], v[24:25] op_sel_hi:[1,0,1] neg_lo:[0,1,0] neg_hi:[0,1,0]
	v_pk_fma_f32 v[26:27], v[94:95], v[30:31], v[26:27] op_sel_hi:[1,0,1] neg_lo:[0,1,0] neg_hi:[0,1,0]
	v_add_f32_e32 v39, v32, v13
	ds_write_b32 v102, v39 offset:2176
	ds_read_b128 v[148:151], v195 offset:5120
	ds_read_b128 v[160:163], v195 offset:37888
	ds_read_b128 v[172:175], v195 offset:29696
	ds_read_b128 v[184:187], v195 offset:21504
	ds_read_b128 v[92:95], v195 offset:13312
	ds_read_b64 v[12:13], v196 offset:10240
	ds_read_b64 v[14:15], v36 offset:10240
	s_waitcnt lgkmcnt(15)
	v_mul_f32_e32 v34, v24, v140
	v_mul_f32_e32 v38, v24, v152
	v_mul_f32_e32 v33, v20, v140
	v_mul_f32_e32 v35, v20, v152
	v_fmac_f32_e32 v34, v25, v141
	v_fmac_f32_e32 v38, v25, v153
	v_fmac_f32_e32 v33, v21, v141
	v_fmac_f32_e32 v35, v21, v153
	v_fmac_f32_e32 v34, v26, v142
	v_fmac_f32_e32 v38, v26, v154
	v_fmac_f32_e32 v33, v22, v142
	v_fmac_f32_e32 v35, v22, v154
	v_fmac_f32_e32 v34, v27, v143
	v_fmac_f32_e32 v38, v27, v155
	v_fmac_f32_e32 v33, v23, v143
	v_fmac_f32_e32 v35, v23, v155
	v_add_f32_dpp v28, v34, v33 row_half_mirror row_mask:0xf bank_mask:0xf
	v_add_f32_dpp v32, v38, v35 row_half_mirror row_mask:0xf bank_mask:0xf
	v_pk_mul_f32 v[20:21], v[20:21], v[164:165]
	v_add_f32_dpp v28, v28, v28 row_ror:8 row_mask:0xf bank_mask:0xf
	v_add_f32_dpp v32, v32, v32 row_ror:8 row_mask:0xf bank_mask:0xf
	v_pk_mul_f32 v[22:23], v[22:23], v[166:167]
	v_add_f32_dpp v28, v28, v28 quad_perm:[1,0,3,2] row_mask:0xf bank_mask:0xf
	v_add_f32_dpp v32, v32, v32 quad_perm:[1,0,3,2] row_mask:0xf bank_mask:0xf
	v_pk_mul_f32 v[24:25], v[24:25], v[164:165]
	v_add_f32_dpp v28, v28, v28 quad_perm:[2,3,0,1] row_mask:0xf bank_mask:0xf
	v_add_f32_dpp v32, v32, v32 quad_perm:[2,3,0,1] row_mask:0xf bank_mask:0xf
	v_pk_mul_f32 v[26:27], v[26:27], v[166:167]
	v_pk_fma_f32 v[20:21], v[176:177], v[4:5], v[20:21] op_sel_hi:[1,0,1]
	v_mov_b32_dpp v30, v28 row_half_mirror row_mask:0xf bank_mask:0xf
	v_pk_fma_f32 v[22:23], v[178:179], v[4:5], v[22:23] op_sel_hi:[1,0,1]
	v_pk_fma_f32 v[24:25], v[176:177], v[6:7], v[24:25] op_sel_hi:[1,0,1]
	v_pk_fma_f32 v[26:27], v[178:179], v[6:7], v[26:27] op_sel_hi:[1,0,1]
	v_pk_fma_f32 v[20:21], v[84:85], v[28:29], v[20:21] op_sel_hi:[1,0,1] neg_lo:[0,1,0] neg_hi:[0,1,0]
	v_pk_fma_f32 v[22:23], v[86:87], v[28:29], v[22:23] op_sel_hi:[1,0,1] neg_lo:[0,1,0] neg_hi:[0,1,0]
	v_pk_fma_f32 v[24:25], v[84:85], v[30:31], v[24:25] op_sel_hi:[1,0,1] neg_lo:[0,1,0] neg_hi:[0,1,0]
	v_pk_fma_f32 v[26:27], v[86:87], v[30:31], v[26:27] op_sel_hi:[1,0,1] neg_lo:[0,1,0] neg_hi:[0,1,0]
	v_add_f32_e32 v39, v32, v5
	ds_write_b32 v102, v39 offset:2304
	ds_read_b128 v[140:143], v195 offset:5376
	ds_read_b128 v[152:155], v195 offset:38144
	ds_read_b128 v[164:167], v195 offset:29952
	ds_read_b128 v[176:179], v195 offset:21760
	ds_read_b128 v[84:87], v195 offset:13568
	ds_read_b64 v[4:5], v196 offset:10752
	ds_read_b64 v[6:7], v36 offset:10752
	s_waitcnt lgkmcnt(15)
	v_mul_f32_e32 v34, v24, v144
	v_mul_f32_e32 v38, v24, v156
	v_mul_f32_e32 v33, v20, v144
	v_mul_f32_e32 v35, v20, v156
	v_fmac_f32_e32 v34, v25, v145
	v_fmac_f32_e32 v38, v25, v157
	v_fmac_f32_e32 v33, v21, v145
	v_fmac_f32_e32 v35, v21, v157
	v_fmac_f32_e32 v34, v26, v146
	v_fmac_f32_e32 v38, v26, v158
	v_fmac_f32_e32 v33, v22, v146
	v_fmac_f32_e32 v35, v22, v158
	v_fmac_f32_e32 v34, v27, v147
	v_fmac_f32_e32 v38, v27, v159
	v_fmac_f32_e32 v33, v23, v147
	v_fmac_f32_e32 v35, v23, v159
	v_add_f32_dpp v28, v34, v33 row_half_mirror row_mask:0xf bank_mask:0xf
	v_add_f32_dpp v32, v38, v35 row_half_mirror row_mask:0xf bank_mask:0xf
	v_pk_mul_f32 v[20:21], v[20:21], v[168:169]
	v_add_f32_dpp v28, v28, v28 row_ror:8 row_mask:0xf bank_mask:0xf
	v_add_f32_dpp v32, v32, v32 row_ror:8 row_mask:0xf bank_mask:0xf
	v_pk_mul_f32 v[22:23], v[22:23], v[170:171]
	v_add_f32_dpp v28, v28, v28 quad_perm:[1,0,3,2] row_mask:0xf bank_mask:0xf
	v_add_f32_dpp v32, v32, v32 quad_perm:[1,0,3,2] row_mask:0xf bank_mask:0xf
	v_pk_mul_f32 v[24:25], v[24:25], v[168:169]
	v_add_f32_dpp v28, v28, v28 quad_perm:[2,3,0,1] row_mask:0xf bank_mask:0xf
	v_add_f32_dpp v32, v32, v32 quad_perm:[2,3,0,1] row_mask:0xf bank_mask:0xf
	v_pk_mul_f32 v[26:27], v[26:27], v[170:171]
	v_pk_fma_f32 v[20:21], v[180:181], v[8:9], v[20:21] op_sel_hi:[1,0,1]
	v_mov_b32_dpp v30, v28 row_half_mirror row_mask:0xf bank_mask:0xf
	v_pk_fma_f32 v[22:23], v[182:183], v[8:9], v[22:23] op_sel_hi:[1,0,1]
	v_pk_fma_f32 v[24:25], v[180:181], v[10:11], v[24:25] op_sel_hi:[1,0,1]
	v_pk_fma_f32 v[26:27], v[182:183], v[10:11], v[26:27] op_sel_hi:[1,0,1]
	v_pk_fma_f32 v[20:21], v[88:89], v[28:29], v[20:21] op_sel_hi:[1,0,1] neg_lo:[0,1,0] neg_hi:[0,1,0]
	v_pk_fma_f32 v[22:23], v[90:91], v[28:29], v[22:23] op_sel_hi:[1,0,1] neg_lo:[0,1,0] neg_hi:[0,1,0]
	v_pk_fma_f32 v[24:25], v[88:89], v[30:31], v[24:25] op_sel_hi:[1,0,1] neg_lo:[0,1,0] neg_hi:[0,1,0]
	v_pk_fma_f32 v[26:27], v[90:91], v[30:31], v[26:27] op_sel_hi:[1,0,1] neg_lo:[0,1,0] neg_hi:[0,1,0]
	v_add_f32_e32 v39, v32, v9
	ds_write_b32 v102, v39 offset:2432
	ds_read_b128 v[144:147], v195 offset:5632
	ds_read_b128 v[156:159], v195 offset:38400
	ds_read_b128 v[168:171], v195 offset:30208
	ds_read_b128 v[180:183], v195 offset:22016
	ds_read_b128 v[88:91], v195 offset:13824
	ds_read_b64 v[8:9], v196 offset:11264
	ds_read_b64 v[10:11], v36 offset:11264
	s_waitcnt lgkmcnt(15)
	v_mul_f32_e32 v34, v24, v148
	v_mul_f32_e32 v38, v24, v160
	v_mul_f32_e32 v33, v20, v148
	v_mul_f32_e32 v35, v20, v160
	v_fmac_f32_e32 v34, v25, v149
	v_fmac_f32_e32 v38, v25, v161
	v_fmac_f32_e32 v33, v21, v149
	v_fmac_f32_e32 v35, v21, v161
	v_fmac_f32_e32 v34, v26, v150
	v_fmac_f32_e32 v38, v26, v162
	v_fmac_f32_e32 v33, v22, v150
	v_fmac_f32_e32 v35, v22, v162
	v_fmac_f32_e32 v34, v27, v151
	v_fmac_f32_e32 v38, v27, v163
	v_fmac_f32_e32 v33, v23, v151
	v_fmac_f32_e32 v35, v23, v163
	v_add_f32_dpp v28, v34, v33 row_half_mirror row_mask:0xf bank_mask:0xf
	v_add_f32_dpp v32, v38, v35 row_half_mirror row_mask:0xf bank_mask:0xf
	v_pk_mul_f32 v[20:21], v[20:21], v[172:173]
	v_add_f32_dpp v28, v28, v28 row_ror:8 row_mask:0xf bank_mask:0xf
	v_add_f32_dpp v32, v32, v32 row_ror:8 row_mask:0xf bank_mask:0xf
	v_pk_mul_f32 v[22:23], v[22:23], v[174:175]
	v_add_f32_dpp v28, v28, v28 quad_perm:[1,0,3,2] row_mask:0xf bank_mask:0xf
	v_add_f32_dpp v32, v32, v32 quad_perm:[1,0,3,2] row_mask:0xf bank_mask:0xf
	v_pk_mul_f32 v[24:25], v[24:25], v[172:173]
	v_add_f32_dpp v28, v28, v28 quad_perm:[2,3,0,1] row_mask:0xf bank_mask:0xf
	v_add_f32_dpp v32, v32, v32 quad_perm:[2,3,0,1] row_mask:0xf bank_mask:0xf
	v_pk_mul_f32 v[26:27], v[26:27], v[174:175]
	v_pk_fma_f32 v[20:21], v[184:185], v[12:13], v[20:21] op_sel_hi:[1,0,1]
	v_mov_b32_dpp v30, v28 row_half_mirror row_mask:0xf bank_mask:0xf
	v_pk_fma_f32 v[22:23], v[186:187], v[12:13], v[22:23] op_sel_hi:[1,0,1]
	v_pk_fma_f32 v[24:25], v[184:185], v[14:15], v[24:25] op_sel_hi:[1,0,1]
	v_pk_fma_f32 v[26:27], v[186:187], v[14:15], v[26:27] op_sel_hi:[1,0,1]
	v_pk_fma_f32 v[20:21], v[92:93], v[28:29], v[20:21] op_sel_hi:[1,0,1] neg_lo:[0,1,0] neg_hi:[0,1,0]
	v_pk_fma_f32 v[22:23], v[94:95], v[28:29], v[22:23] op_sel_hi:[1,0,1] neg_lo:[0,1,0] neg_hi:[0,1,0]
	v_pk_fma_f32 v[24:25], v[92:93], v[30:31], v[24:25] op_sel_hi:[1,0,1] neg_lo:[0,1,0] neg_hi:[0,1,0]
	v_pk_fma_f32 v[26:27], v[94:95], v[30:31], v[26:27] op_sel_hi:[1,0,1] neg_lo:[0,1,0] neg_hi:[0,1,0]
	v_add_f32_e32 v39, v32, v13
	ds_write_b32 v102, v39 offset:2560
	ds_read_b128 v[148:151], v195 offset:5888
	ds_read_b128 v[160:163], v195 offset:38656
	ds_read_b128 v[172:175], v195 offset:30464
	ds_read_b128 v[184:187], v195 offset:22272
	ds_read_b128 v[92:95], v195 offset:14080
	ds_read_b64 v[12:13], v196 offset:11776
	ds_read_b64 v[14:15], v36 offset:11776
	s_waitcnt lgkmcnt(15)
	v_mul_f32_e32 v34, v24, v140
	v_mul_f32_e32 v38, v24, v152
	v_mul_f32_e32 v33, v20, v140
	v_mul_f32_e32 v35, v20, v152
	v_fmac_f32_e32 v34, v25, v141
	v_fmac_f32_e32 v38, v25, v153
	v_fmac_f32_e32 v33, v21, v141
	v_fmac_f32_e32 v35, v21, v153
	v_fmac_f32_e32 v34, v26, v142
	v_fmac_f32_e32 v38, v26, v154
	v_fmac_f32_e32 v33, v22, v142
	v_fmac_f32_e32 v35, v22, v154
	v_fmac_f32_e32 v34, v27, v143
	v_fmac_f32_e32 v38, v27, v155
	v_fmac_f32_e32 v33, v23, v143
	v_fmac_f32_e32 v35, v23, v155
	v_add_f32_dpp v28, v34, v33 row_half_mirror row_mask:0xf bank_mask:0xf
	v_add_f32_dpp v32, v38, v35 row_half_mirror row_mask:0xf bank_mask:0xf
	v_pk_mul_f32 v[20:21], v[20:21], v[164:165]
	v_add_f32_dpp v28, v28, v28 row_ror:8 row_mask:0xf bank_mask:0xf
	v_add_f32_dpp v32, v32, v32 row_ror:8 row_mask:0xf bank_mask:0xf
	v_pk_mul_f32 v[22:23], v[22:23], v[166:167]
	v_add_f32_dpp v28, v28, v28 quad_perm:[1,0,3,2] row_mask:0xf bank_mask:0xf
	v_add_f32_dpp v32, v32, v32 quad_perm:[1,0,3,2] row_mask:0xf bank_mask:0xf
	v_pk_mul_f32 v[24:25], v[24:25], v[164:165]
	v_add_f32_dpp v28, v28, v28 quad_perm:[2,3,0,1] row_mask:0xf bank_mask:0xf
	v_add_f32_dpp v32, v32, v32 quad_perm:[2,3,0,1] row_mask:0xf bank_mask:0xf
	v_pk_mul_f32 v[26:27], v[26:27], v[166:167]
	v_pk_fma_f32 v[20:21], v[176:177], v[4:5], v[20:21] op_sel_hi:[1,0,1]
	v_mov_b32_dpp v30, v28 row_half_mirror row_mask:0xf bank_mask:0xf
	v_pk_fma_f32 v[22:23], v[178:179], v[4:5], v[22:23] op_sel_hi:[1,0,1]
	v_pk_fma_f32 v[24:25], v[176:177], v[6:7], v[24:25] op_sel_hi:[1,0,1]
	v_pk_fma_f32 v[26:27], v[178:179], v[6:7], v[26:27] op_sel_hi:[1,0,1]
	v_pk_fma_f32 v[20:21], v[84:85], v[28:29], v[20:21] op_sel_hi:[1,0,1] neg_lo:[0,1,0] neg_hi:[0,1,0]
	v_pk_fma_f32 v[22:23], v[86:87], v[28:29], v[22:23] op_sel_hi:[1,0,1] neg_lo:[0,1,0] neg_hi:[0,1,0]
	v_pk_fma_f32 v[24:25], v[84:85], v[30:31], v[24:25] op_sel_hi:[1,0,1] neg_lo:[0,1,0] neg_hi:[0,1,0]
	v_pk_fma_f32 v[26:27], v[86:87], v[30:31], v[26:27] op_sel_hi:[1,0,1] neg_lo:[0,1,0] neg_hi:[0,1,0]
	v_add_f32_e32 v39, v32, v5
	ds_write_b32 v102, v39 offset:2688
	ds_read_b128 v[140:143], v195 offset:6144
	ds_read_b128 v[152:155], v195 offset:38912
	ds_read_b128 v[164:167], v195 offset:30720
	ds_read_b128 v[176:179], v195 offset:22528
	ds_read_b128 v[84:87], v195 offset:14336
	ds_read_b64 v[4:5], v196 offset:12288
	ds_read_b64 v[6:7], v36 offset:12288
	s_waitcnt lgkmcnt(15)
	v_mul_f32_e32 v34, v24, v144
	v_mul_f32_e32 v38, v24, v156
	v_mul_f32_e32 v33, v20, v144
	v_mul_f32_e32 v35, v20, v156
	v_fmac_f32_e32 v34, v25, v145
	v_fmac_f32_e32 v38, v25, v157
	v_fmac_f32_e32 v33, v21, v145
	v_fmac_f32_e32 v35, v21, v157
	v_fmac_f32_e32 v34, v26, v146
	v_fmac_f32_e32 v38, v26, v158
	v_fmac_f32_e32 v33, v22, v146
	v_fmac_f32_e32 v35, v22, v158
	v_fmac_f32_e32 v34, v27, v147
	v_fmac_f32_e32 v38, v27, v159
	v_fmac_f32_e32 v33, v23, v147
	v_fmac_f32_e32 v35, v23, v159
	v_add_f32_dpp v28, v34, v33 row_half_mirror row_mask:0xf bank_mask:0xf
	v_add_f32_dpp v32, v38, v35 row_half_mirror row_mask:0xf bank_mask:0xf
	v_pk_mul_f32 v[20:21], v[20:21], v[168:169]
	v_add_f32_dpp v28, v28, v28 row_ror:8 row_mask:0xf bank_mask:0xf
	v_add_f32_dpp v32, v32, v32 row_ror:8 row_mask:0xf bank_mask:0xf
	v_pk_mul_f32 v[22:23], v[22:23], v[170:171]
	v_add_f32_dpp v28, v28, v28 quad_perm:[1,0,3,2] row_mask:0xf bank_mask:0xf
	v_add_f32_dpp v32, v32, v32 quad_perm:[1,0,3,2] row_mask:0xf bank_mask:0xf
	v_pk_mul_f32 v[24:25], v[24:25], v[168:169]
	v_add_f32_dpp v28, v28, v28 quad_perm:[2,3,0,1] row_mask:0xf bank_mask:0xf
	v_add_f32_dpp v32, v32, v32 quad_perm:[2,3,0,1] row_mask:0xf bank_mask:0xf
	v_pk_mul_f32 v[26:27], v[26:27], v[170:171]
	v_pk_fma_f32 v[20:21], v[180:181], v[8:9], v[20:21] op_sel_hi:[1,0,1]
	v_mov_b32_dpp v30, v28 row_half_mirror row_mask:0xf bank_mask:0xf
	v_pk_fma_f32 v[22:23], v[182:183], v[8:9], v[22:23] op_sel_hi:[1,0,1]
	v_pk_fma_f32 v[24:25], v[180:181], v[10:11], v[24:25] op_sel_hi:[1,0,1]
	v_pk_fma_f32 v[26:27], v[182:183], v[10:11], v[26:27] op_sel_hi:[1,0,1]
	v_pk_fma_f32 v[20:21], v[88:89], v[28:29], v[20:21] op_sel_hi:[1,0,1] neg_lo:[0,1,0] neg_hi:[0,1,0]
	v_pk_fma_f32 v[22:23], v[90:91], v[28:29], v[22:23] op_sel_hi:[1,0,1] neg_lo:[0,1,0] neg_hi:[0,1,0]
	v_pk_fma_f32 v[24:25], v[88:89], v[30:31], v[24:25] op_sel_hi:[1,0,1] neg_lo:[0,1,0] neg_hi:[0,1,0]
	v_pk_fma_f32 v[26:27], v[90:91], v[30:31], v[26:27] op_sel_hi:[1,0,1] neg_lo:[0,1,0] neg_hi:[0,1,0]
	v_add_f32_e32 v39, v32, v9
	ds_write_b32 v102, v39 offset:2816
	ds_read_b128 v[144:147], v195 offset:6400
	ds_read_b128 v[156:159], v195 offset:39168
	ds_read_b128 v[168:171], v195 offset:30976
	ds_read_b128 v[180:183], v195 offset:22784
	ds_read_b128 v[88:91], v195 offset:14592
	ds_read_b64 v[8:9], v196 offset:12800
	ds_read_b64 v[10:11], v36 offset:12800
	s_waitcnt lgkmcnt(15)
	v_mul_f32_e32 v34, v24, v148
	v_mul_f32_e32 v38, v24, v160
	v_mul_f32_e32 v33, v20, v148
	v_mul_f32_e32 v35, v20, v160
	v_fmac_f32_e32 v34, v25, v149
	v_fmac_f32_e32 v38, v25, v161
	v_fmac_f32_e32 v33, v21, v149
	v_fmac_f32_e32 v35, v21, v161
	v_fmac_f32_e32 v34, v26, v150
	v_fmac_f32_e32 v38, v26, v162
	v_fmac_f32_e32 v33, v22, v150
	v_fmac_f32_e32 v35, v22, v162
	v_fmac_f32_e32 v34, v27, v151
	v_fmac_f32_e32 v38, v27, v163
	v_fmac_f32_e32 v33, v23, v151
	v_fmac_f32_e32 v35, v23, v163
	v_add_f32_dpp v28, v34, v33 row_half_mirror row_mask:0xf bank_mask:0xf
	v_add_f32_dpp v32, v38, v35 row_half_mirror row_mask:0xf bank_mask:0xf
	v_pk_mul_f32 v[20:21], v[20:21], v[172:173]
	v_add_f32_dpp v28, v28, v28 row_ror:8 row_mask:0xf bank_mask:0xf
	v_add_f32_dpp v32, v32, v32 row_ror:8 row_mask:0xf bank_mask:0xf
	v_pk_mul_f32 v[22:23], v[22:23], v[174:175]
	v_add_f32_dpp v28, v28, v28 quad_perm:[1,0,3,2] row_mask:0xf bank_mask:0xf
	v_add_f32_dpp v32, v32, v32 quad_perm:[1,0,3,2] row_mask:0xf bank_mask:0xf
	v_pk_mul_f32 v[24:25], v[24:25], v[172:173]
	v_add_f32_dpp v28, v28, v28 quad_perm:[2,3,0,1] row_mask:0xf bank_mask:0xf
	v_add_f32_dpp v32, v32, v32 quad_perm:[2,3,0,1] row_mask:0xf bank_mask:0xf
	v_pk_mul_f32 v[26:27], v[26:27], v[174:175]
	v_pk_fma_f32 v[20:21], v[184:185], v[12:13], v[20:21] op_sel_hi:[1,0,1]
	v_mov_b32_dpp v30, v28 row_half_mirror row_mask:0xf bank_mask:0xf
	v_pk_fma_f32 v[22:23], v[186:187], v[12:13], v[22:23] op_sel_hi:[1,0,1]
	v_pk_fma_f32 v[24:25], v[184:185], v[14:15], v[24:25] op_sel_hi:[1,0,1]
	v_pk_fma_f32 v[26:27], v[186:187], v[14:15], v[26:27] op_sel_hi:[1,0,1]
	v_pk_fma_f32 v[20:21], v[92:93], v[28:29], v[20:21] op_sel_hi:[1,0,1] neg_lo:[0,1,0] neg_hi:[0,1,0]
	v_pk_fma_f32 v[22:23], v[94:95], v[28:29], v[22:23] op_sel_hi:[1,0,1] neg_lo:[0,1,0] neg_hi:[0,1,0]
	v_pk_fma_f32 v[24:25], v[92:93], v[30:31], v[24:25] op_sel_hi:[1,0,1] neg_lo:[0,1,0] neg_hi:[0,1,0]
	v_pk_fma_f32 v[26:27], v[94:95], v[30:31], v[26:27] op_sel_hi:[1,0,1] neg_lo:[0,1,0] neg_hi:[0,1,0]
	v_add_f32_e32 v39, v32, v13
	ds_write_b32 v102, v39 offset:2944
	ds_read_b128 v[148:151], v195 offset:6656
	ds_read_b128 v[160:163], v195 offset:39424
	ds_read_b128 v[172:175], v195 offset:31232
	ds_read_b128 v[184:187], v195 offset:23040
	ds_read_b128 v[92:95], v195 offset:14848
	ds_read_b64 v[12:13], v196 offset:13312
	ds_read_b64 v[14:15], v36 offset:13312
	s_waitcnt lgkmcnt(15)
	v_mul_f32_e32 v34, v24, v140
	v_mul_f32_e32 v38, v24, v152
	v_mul_f32_e32 v33, v20, v140
	v_mul_f32_e32 v35, v20, v152
	v_fmac_f32_e32 v34, v25, v141
	v_fmac_f32_e32 v38, v25, v153
	v_fmac_f32_e32 v33, v21, v141
	v_fmac_f32_e32 v35, v21, v153
	v_fmac_f32_e32 v34, v26, v142
	v_fmac_f32_e32 v38, v26, v154
	v_fmac_f32_e32 v33, v22, v142
	v_fmac_f32_e32 v35, v22, v154
	v_fmac_f32_e32 v34, v27, v143
	v_fmac_f32_e32 v38, v27, v155
	v_fmac_f32_e32 v33, v23, v143
	v_fmac_f32_e32 v35, v23, v155
	v_add_f32_dpp v28, v34, v33 row_half_mirror row_mask:0xf bank_mask:0xf
	v_add_f32_dpp v32, v38, v35 row_half_mirror row_mask:0xf bank_mask:0xf
	v_pk_mul_f32 v[20:21], v[20:21], v[164:165]
	v_add_f32_dpp v28, v28, v28 row_ror:8 row_mask:0xf bank_mask:0xf
	v_add_f32_dpp v32, v32, v32 row_ror:8 row_mask:0xf bank_mask:0xf
	v_pk_mul_f32 v[22:23], v[22:23], v[166:167]
	v_add_f32_dpp v28, v28, v28 quad_perm:[1,0,3,2] row_mask:0xf bank_mask:0xf
	v_add_f32_dpp v32, v32, v32 quad_perm:[1,0,3,2] row_mask:0xf bank_mask:0xf
	v_pk_mul_f32 v[24:25], v[24:25], v[164:165]
	v_add_f32_dpp v28, v28, v28 quad_perm:[2,3,0,1] row_mask:0xf bank_mask:0xf
	v_add_f32_dpp v32, v32, v32 quad_perm:[2,3,0,1] row_mask:0xf bank_mask:0xf
	v_pk_mul_f32 v[26:27], v[26:27], v[166:167]
	v_pk_fma_f32 v[20:21], v[176:177], v[4:5], v[20:21] op_sel_hi:[1,0,1]
	v_mov_b32_dpp v30, v28 row_half_mirror row_mask:0xf bank_mask:0xf
	v_pk_fma_f32 v[22:23], v[178:179], v[4:5], v[22:23] op_sel_hi:[1,0,1]
	v_pk_fma_f32 v[24:25], v[176:177], v[6:7], v[24:25] op_sel_hi:[1,0,1]
	v_pk_fma_f32 v[26:27], v[178:179], v[6:7], v[26:27] op_sel_hi:[1,0,1]
	v_pk_fma_f32 v[20:21], v[84:85], v[28:29], v[20:21] op_sel_hi:[1,0,1] neg_lo:[0,1,0] neg_hi:[0,1,0]
	v_pk_fma_f32 v[22:23], v[86:87], v[28:29], v[22:23] op_sel_hi:[1,0,1] neg_lo:[0,1,0] neg_hi:[0,1,0]
	v_pk_fma_f32 v[24:25], v[84:85], v[30:31], v[24:25] op_sel_hi:[1,0,1] neg_lo:[0,1,0] neg_hi:[0,1,0]
	v_pk_fma_f32 v[26:27], v[86:87], v[30:31], v[26:27] op_sel_hi:[1,0,1] neg_lo:[0,1,0] neg_hi:[0,1,0]
	v_add_f32_e32 v39, v32, v5
	ds_write_b32 v102, v39 offset:3072
	ds_read_b128 v[140:143], v195 offset:6912
	ds_read_b128 v[152:155], v195 offset:39680
	ds_read_b128 v[164:167], v195 offset:31488
	ds_read_b128 v[176:179], v195 offset:23296
	ds_read_b128 v[84:87], v195 offset:15104
	ds_read_b64 v[4:5], v196 offset:13824
	ds_read_b64 v[6:7], v36 offset:13824
	s_waitcnt lgkmcnt(15)
	v_mul_f32_e32 v34, v24, v144
	v_mul_f32_e32 v38, v24, v156
	v_mul_f32_e32 v33, v20, v144
	v_mul_f32_e32 v35, v20, v156
	v_fmac_f32_e32 v34, v25, v145
	v_fmac_f32_e32 v38, v25, v157
	v_fmac_f32_e32 v33, v21, v145
	v_fmac_f32_e32 v35, v21, v157
	v_fmac_f32_e32 v34, v26, v146
	v_fmac_f32_e32 v38, v26, v158
	v_fmac_f32_e32 v33, v22, v146
	v_fmac_f32_e32 v35, v22, v158
	v_fmac_f32_e32 v34, v27, v147
	v_fmac_f32_e32 v38, v27, v159
	v_fmac_f32_e32 v33, v23, v147
	v_fmac_f32_e32 v35, v23, v159
	v_add_f32_dpp v28, v34, v33 row_half_mirror row_mask:0xf bank_mask:0xf
	v_add_f32_dpp v32, v38, v35 row_half_mirror row_mask:0xf bank_mask:0xf
	v_pk_mul_f32 v[20:21], v[20:21], v[168:169]
	v_add_f32_dpp v28, v28, v28 row_ror:8 row_mask:0xf bank_mask:0xf
	v_add_f32_dpp v32, v32, v32 row_ror:8 row_mask:0xf bank_mask:0xf
	v_pk_mul_f32 v[22:23], v[22:23], v[170:171]
	v_add_f32_dpp v28, v28, v28 quad_perm:[1,0,3,2] row_mask:0xf bank_mask:0xf
	v_add_f32_dpp v32, v32, v32 quad_perm:[1,0,3,2] row_mask:0xf bank_mask:0xf
	v_pk_mul_f32 v[24:25], v[24:25], v[168:169]
	v_add_f32_dpp v28, v28, v28 quad_perm:[2,3,0,1] row_mask:0xf bank_mask:0xf
	v_add_f32_dpp v32, v32, v32 quad_perm:[2,3,0,1] row_mask:0xf bank_mask:0xf
	v_pk_mul_f32 v[26:27], v[26:27], v[170:171]
	v_pk_fma_f32 v[20:21], v[180:181], v[8:9], v[20:21] op_sel_hi:[1,0,1]
	v_mov_b32_dpp v30, v28 row_half_mirror row_mask:0xf bank_mask:0xf
	v_pk_fma_f32 v[22:23], v[182:183], v[8:9], v[22:23] op_sel_hi:[1,0,1]
	v_pk_fma_f32 v[24:25], v[180:181], v[10:11], v[24:25] op_sel_hi:[1,0,1]
	v_pk_fma_f32 v[26:27], v[182:183], v[10:11], v[26:27] op_sel_hi:[1,0,1]
	v_pk_fma_f32 v[20:21], v[88:89], v[28:29], v[20:21] op_sel_hi:[1,0,1] neg_lo:[0,1,0] neg_hi:[0,1,0]
	v_pk_fma_f32 v[22:23], v[90:91], v[28:29], v[22:23] op_sel_hi:[1,0,1] neg_lo:[0,1,0] neg_hi:[0,1,0]
	v_pk_fma_f32 v[24:25], v[88:89], v[30:31], v[24:25] op_sel_hi:[1,0,1] neg_lo:[0,1,0] neg_hi:[0,1,0]
	v_pk_fma_f32 v[26:27], v[90:91], v[30:31], v[26:27] op_sel_hi:[1,0,1] neg_lo:[0,1,0] neg_hi:[0,1,0]
	v_add_f32_e32 v39, v32, v9
	ds_write_b32 v102, v39 offset:3200
	ds_read_b128 v[144:147], v195 offset:7168
	ds_read_b128 v[156:159], v195 offset:39936
	ds_read_b128 v[168:171], v195 offset:31744
	ds_read_b128 v[180:183], v195 offset:23552
	ds_read_b128 v[88:91], v195 offset:15360
	ds_read_b64 v[8:9], v196 offset:14336
	ds_read_b64 v[10:11], v36 offset:14336
	s_waitcnt lgkmcnt(15)
	v_mul_f32_e32 v34, v24, v148
	v_mul_f32_e32 v38, v24, v160
	v_mul_f32_e32 v33, v20, v148
	v_mul_f32_e32 v35, v20, v160
	v_fmac_f32_e32 v34, v25, v149
	v_fmac_f32_e32 v38, v25, v161
	v_fmac_f32_e32 v33, v21, v149
	v_fmac_f32_e32 v35, v21, v161
	v_fmac_f32_e32 v34, v26, v150
	v_fmac_f32_e32 v38, v26, v162
	v_fmac_f32_e32 v33, v22, v150
	v_fmac_f32_e32 v35, v22, v162
	v_fmac_f32_e32 v34, v27, v151
	v_fmac_f32_e32 v38, v27, v163
	v_fmac_f32_e32 v33, v23, v151
	v_fmac_f32_e32 v35, v23, v163
	v_add_f32_dpp v28, v34, v33 row_half_mirror row_mask:0xf bank_mask:0xf
	v_add_f32_dpp v32, v38, v35 row_half_mirror row_mask:0xf bank_mask:0xf
	v_pk_mul_f32 v[20:21], v[20:21], v[172:173]
	v_add_f32_dpp v28, v28, v28 row_ror:8 row_mask:0xf bank_mask:0xf
	v_add_f32_dpp v32, v32, v32 row_ror:8 row_mask:0xf bank_mask:0xf
	v_pk_mul_f32 v[22:23], v[22:23], v[174:175]
	v_add_f32_dpp v28, v28, v28 quad_perm:[1,0,3,2] row_mask:0xf bank_mask:0xf
	v_add_f32_dpp v32, v32, v32 quad_perm:[1,0,3,2] row_mask:0xf bank_mask:0xf
	v_pk_mul_f32 v[24:25], v[24:25], v[172:173]
	v_add_f32_dpp v28, v28, v28 quad_perm:[2,3,0,1] row_mask:0xf bank_mask:0xf
	v_add_f32_dpp v32, v32, v32 quad_perm:[2,3,0,1] row_mask:0xf bank_mask:0xf
	v_pk_mul_f32 v[26:27], v[26:27], v[174:175]
	v_pk_fma_f32 v[20:21], v[184:185], v[12:13], v[20:21] op_sel_hi:[1,0,1]
	v_mov_b32_dpp v30, v28 row_half_mirror row_mask:0xf bank_mask:0xf
	v_pk_fma_f32 v[22:23], v[186:187], v[12:13], v[22:23] op_sel_hi:[1,0,1]
	v_pk_fma_f32 v[24:25], v[184:185], v[14:15], v[24:25] op_sel_hi:[1,0,1]
	v_pk_fma_f32 v[26:27], v[186:187], v[14:15], v[26:27] op_sel_hi:[1,0,1]
	v_pk_fma_f32 v[20:21], v[92:93], v[28:29], v[20:21] op_sel_hi:[1,0,1] neg_lo:[0,1,0] neg_hi:[0,1,0]
	v_pk_fma_f32 v[22:23], v[94:95], v[28:29], v[22:23] op_sel_hi:[1,0,1] neg_lo:[0,1,0] neg_hi:[0,1,0]
	v_pk_fma_f32 v[24:25], v[92:93], v[30:31], v[24:25] op_sel_hi:[1,0,1] neg_lo:[0,1,0] neg_hi:[0,1,0]
	v_pk_fma_f32 v[26:27], v[94:95], v[30:31], v[26:27] op_sel_hi:[1,0,1] neg_lo:[0,1,0] neg_hi:[0,1,0]
	v_add_f32_e32 v39, v32, v13
	ds_write_b32 v102, v39 offset:3328
	ds_read_b128 v[148:151], v195 offset:7424
	ds_read_b128 v[160:163], v195 offset:40192
	ds_read_b128 v[172:175], v195 offset:32000
	ds_read_b128 v[184:187], v195 offset:23808
	ds_read_b128 v[92:95], v195 offset:15616
	ds_read_b64 v[12:13], v196 offset:14848
	ds_read_b64 v[14:15], v36 offset:14848
	s_waitcnt lgkmcnt(15)
	v_mul_f32_e32 v34, v24, v140
	v_mul_f32_e32 v38, v24, v152
	v_mul_f32_e32 v33, v20, v140
	v_mul_f32_e32 v35, v20, v152
	v_fmac_f32_e32 v34, v25, v141
	v_fmac_f32_e32 v38, v25, v153
	v_fmac_f32_e32 v33, v21, v141
	v_fmac_f32_e32 v35, v21, v153
	v_fmac_f32_e32 v34, v26, v142
	v_fmac_f32_e32 v38, v26, v154
	v_fmac_f32_e32 v33, v22, v142
	v_fmac_f32_e32 v35, v22, v154
	v_fmac_f32_e32 v34, v27, v143
	v_fmac_f32_e32 v38, v27, v155
	v_fmac_f32_e32 v33, v23, v143
	v_fmac_f32_e32 v35, v23, v155
	v_add_f32_dpp v28, v34, v33 row_half_mirror row_mask:0xf bank_mask:0xf
	v_add_f32_dpp v32, v38, v35 row_half_mirror row_mask:0xf bank_mask:0xf
	v_pk_mul_f32 v[20:21], v[20:21], v[164:165]
	v_add_f32_dpp v28, v28, v28 row_ror:8 row_mask:0xf bank_mask:0xf
	v_add_f32_dpp v32, v32, v32 row_ror:8 row_mask:0xf bank_mask:0xf
	v_pk_mul_f32 v[22:23], v[22:23], v[166:167]
	v_add_f32_dpp v28, v28, v28 quad_perm:[1,0,3,2] row_mask:0xf bank_mask:0xf
	v_add_f32_dpp v32, v32, v32 quad_perm:[1,0,3,2] row_mask:0xf bank_mask:0xf
	v_pk_mul_f32 v[24:25], v[24:25], v[164:165]
	v_add_f32_dpp v28, v28, v28 quad_perm:[2,3,0,1] row_mask:0xf bank_mask:0xf
	v_add_f32_dpp v32, v32, v32 quad_perm:[2,3,0,1] row_mask:0xf bank_mask:0xf
	v_pk_mul_f32 v[26:27], v[26:27], v[166:167]
	v_pk_fma_f32 v[20:21], v[176:177], v[4:5], v[20:21] op_sel_hi:[1,0,1]
	v_mov_b32_dpp v30, v28 row_half_mirror row_mask:0xf bank_mask:0xf
	v_pk_fma_f32 v[22:23], v[178:179], v[4:5], v[22:23] op_sel_hi:[1,0,1]
	v_pk_fma_f32 v[24:25], v[176:177], v[6:7], v[24:25] op_sel_hi:[1,0,1]
	v_pk_fma_f32 v[26:27], v[178:179], v[6:7], v[26:27] op_sel_hi:[1,0,1]
	v_pk_fma_f32 v[20:21], v[84:85], v[28:29], v[20:21] op_sel_hi:[1,0,1] neg_lo:[0,1,0] neg_hi:[0,1,0]
	v_pk_fma_f32 v[22:23], v[86:87], v[28:29], v[22:23] op_sel_hi:[1,0,1] neg_lo:[0,1,0] neg_hi:[0,1,0]
	v_pk_fma_f32 v[24:25], v[84:85], v[30:31], v[24:25] op_sel_hi:[1,0,1] neg_lo:[0,1,0] neg_hi:[0,1,0]
	v_pk_fma_f32 v[26:27], v[86:87], v[30:31], v[26:27] op_sel_hi:[1,0,1] neg_lo:[0,1,0] neg_hi:[0,1,0]
	v_add_f32_e32 v39, v32, v5
	ds_write_b32 v102, v39 offset:3456
	ds_read_b128 v[140:143], v195 offset:7680
	ds_read_b128 v[152:155], v195 offset:40448
	ds_read_b128 v[164:167], v195 offset:32256
	ds_read_b128 v[176:179], v195 offset:24064
	ds_read_b128 v[84:87], v195 offset:15872
	ds_read_b64 v[4:5], v196 offset:15360
	ds_read_b64 v[6:7], v36 offset:15360
	s_waitcnt lgkmcnt(15)
	v_mul_f32_e32 v34, v24, v144
	v_mul_f32_e32 v38, v24, v156
	v_mul_f32_e32 v33, v20, v144
	v_mul_f32_e32 v35, v20, v156
	v_fmac_f32_e32 v34, v25, v145
	v_fmac_f32_e32 v38, v25, v157
	v_fmac_f32_e32 v33, v21, v145
	v_fmac_f32_e32 v35, v21, v157
	v_fmac_f32_e32 v34, v26, v146
	v_fmac_f32_e32 v38, v26, v158
	v_fmac_f32_e32 v33, v22, v146
	v_fmac_f32_e32 v35, v22, v158
	v_fmac_f32_e32 v34, v27, v147
	v_fmac_f32_e32 v38, v27, v159
	v_fmac_f32_e32 v33, v23, v147
	v_fmac_f32_e32 v35, v23, v159
	v_add_f32_dpp v28, v34, v33 row_half_mirror row_mask:0xf bank_mask:0xf
	v_add_f32_dpp v32, v38, v35 row_half_mirror row_mask:0xf bank_mask:0xf
	v_pk_mul_f32 v[20:21], v[20:21], v[168:169]
	v_add_f32_dpp v28, v28, v28 row_ror:8 row_mask:0xf bank_mask:0xf
	v_add_f32_dpp v32, v32, v32 row_ror:8 row_mask:0xf bank_mask:0xf
	v_pk_mul_f32 v[22:23], v[22:23], v[170:171]
	v_add_f32_dpp v28, v28, v28 quad_perm:[1,0,3,2] row_mask:0xf bank_mask:0xf
	v_add_f32_dpp v32, v32, v32 quad_perm:[1,0,3,2] row_mask:0xf bank_mask:0xf
	v_pk_mul_f32 v[24:25], v[24:25], v[168:169]
	v_add_f32_dpp v28, v28, v28 quad_perm:[2,3,0,1] row_mask:0xf bank_mask:0xf
	v_add_f32_dpp v32, v32, v32 quad_perm:[2,3,0,1] row_mask:0xf bank_mask:0xf
	v_pk_mul_f32 v[26:27], v[26:27], v[170:171]
	v_pk_fma_f32 v[20:21], v[180:181], v[8:9], v[20:21] op_sel_hi:[1,0,1]
	v_mov_b32_dpp v30, v28 row_half_mirror row_mask:0xf bank_mask:0xf
	v_pk_fma_f32 v[22:23], v[182:183], v[8:9], v[22:23] op_sel_hi:[1,0,1]
	v_pk_fma_f32 v[24:25], v[180:181], v[10:11], v[24:25] op_sel_hi:[1,0,1]
	v_pk_fma_f32 v[26:27], v[182:183], v[10:11], v[26:27] op_sel_hi:[1,0,1]
	v_pk_fma_f32 v[20:21], v[88:89], v[28:29], v[20:21] op_sel_hi:[1,0,1] neg_lo:[0,1,0] neg_hi:[0,1,0]
	v_pk_fma_f32 v[22:23], v[90:91], v[28:29], v[22:23] op_sel_hi:[1,0,1] neg_lo:[0,1,0] neg_hi:[0,1,0]
	v_pk_fma_f32 v[24:25], v[88:89], v[30:31], v[24:25] op_sel_hi:[1,0,1] neg_lo:[0,1,0] neg_hi:[0,1,0]
	v_pk_fma_f32 v[26:27], v[90:91], v[30:31], v[26:27] op_sel_hi:[1,0,1] neg_lo:[0,1,0] neg_hi:[0,1,0]
	v_add_f32_e32 v39, v32, v9
	ds_write_b32 v102, v39 offset:3584
	ds_read_b128 v[144:147], v195 offset:7936
	ds_read_b128 v[156:159], v195 offset:40704
	ds_read_b128 v[168:171], v195 offset:32512
	ds_read_b128 v[180:183], v195 offset:24320
	ds_read_b128 v[88:91], v195 offset:16128
	ds_read_b64 v[8:9], v196 offset:15872
	ds_read_b64 v[10:11], v36 offset:15872
	s_waitcnt lgkmcnt(15)
	v_mul_f32_e32 v34, v24, v148
	v_mul_f32_e32 v38, v24, v160
	v_mul_f32_e32 v33, v20, v148
	v_mul_f32_e32 v35, v20, v160
	v_fmac_f32_e32 v34, v25, v149
	v_fmac_f32_e32 v38, v25, v161
	v_fmac_f32_e32 v33, v21, v149
	v_fmac_f32_e32 v35, v21, v161
	v_fmac_f32_e32 v34, v26, v150
	v_fmac_f32_e32 v38, v26, v162
	v_fmac_f32_e32 v33, v22, v150
	v_fmac_f32_e32 v35, v22, v162
	v_fmac_f32_e32 v34, v27, v151
	v_fmac_f32_e32 v38, v27, v163
	v_fmac_f32_e32 v33, v23, v151
	v_fmac_f32_e32 v35, v23, v163
	v_add_f32_dpp v28, v34, v33 row_half_mirror row_mask:0xf bank_mask:0xf
	v_add_f32_dpp v32, v38, v35 row_half_mirror row_mask:0xf bank_mask:0xf
	v_pk_mul_f32 v[20:21], v[20:21], v[172:173]
	v_add_f32_dpp v28, v28, v28 row_ror:8 row_mask:0xf bank_mask:0xf
	v_add_f32_dpp v32, v32, v32 row_ror:8 row_mask:0xf bank_mask:0xf
	v_pk_mul_f32 v[22:23], v[22:23], v[174:175]
	v_add_f32_dpp v28, v28, v28 quad_perm:[1,0,3,2] row_mask:0xf bank_mask:0xf
	v_add_f32_dpp v32, v32, v32 quad_perm:[1,0,3,2] row_mask:0xf bank_mask:0xf
	v_pk_mul_f32 v[24:25], v[24:25], v[172:173]
	v_add_f32_dpp v28, v28, v28 quad_perm:[2,3,0,1] row_mask:0xf bank_mask:0xf
	v_add_f32_dpp v32, v32, v32 quad_perm:[2,3,0,1] row_mask:0xf bank_mask:0xf
	v_pk_mul_f32 v[26:27], v[26:27], v[174:175]
	v_pk_fma_f32 v[20:21], v[184:185], v[12:13], v[20:21] op_sel_hi:[1,0,1]
	v_mov_b32_dpp v30, v28 row_half_mirror row_mask:0xf bank_mask:0xf
	v_pk_fma_f32 v[22:23], v[186:187], v[12:13], v[22:23] op_sel_hi:[1,0,1]
	v_pk_fma_f32 v[24:25], v[184:185], v[14:15], v[24:25] op_sel_hi:[1,0,1]
	v_pk_fma_f32 v[26:27], v[186:187], v[14:15], v[26:27] op_sel_hi:[1,0,1]
	v_pk_fma_f32 v[20:21], v[92:93], v[28:29], v[20:21] op_sel_hi:[1,0,1] neg_lo:[0,1,0] neg_hi:[0,1,0]
	v_pk_fma_f32 v[22:23], v[94:95], v[28:29], v[22:23] op_sel_hi:[1,0,1] neg_lo:[0,1,0] neg_hi:[0,1,0]
	v_pk_fma_f32 v[24:25], v[92:93], v[30:31], v[24:25] op_sel_hi:[1,0,1] neg_lo:[0,1,0] neg_hi:[0,1,0]
	v_pk_fma_f32 v[26:27], v[94:95], v[30:31], v[26:27] op_sel_hi:[1,0,1] neg_lo:[0,1,0] neg_hi:[0,1,0]
	v_add_f32_e32 v39, v32, v13
	ds_write_b32 v102, v39 offset:3712
	s_waitcnt lgkmcnt(9)
	v_mul_f32_e32 v34, v24, v140
	v_mul_f32_e32 v38, v24, v152
	v_mul_f32_e32 v33, v20, v140
	v_mul_f32_e32 v35, v20, v152
	v_fmac_f32_e32 v34, v25, v141
	v_fmac_f32_e32 v38, v25, v153
	v_fmac_f32_e32 v33, v21, v141
	v_fmac_f32_e32 v35, v21, v153
	v_fmac_f32_e32 v34, v26, v142
	v_fmac_f32_e32 v38, v26, v154
	v_fmac_f32_e32 v33, v22, v142
	v_fmac_f32_e32 v35, v22, v154
	v_fmac_f32_e32 v34, v27, v143
	v_fmac_f32_e32 v38, v27, v155
	v_fmac_f32_e32 v33, v23, v143
	v_fmac_f32_e32 v35, v23, v155
	v_add_f32_dpp v28, v34, v33 row_half_mirror row_mask:0xf bank_mask:0xf
	v_add_f32_dpp v32, v38, v35 row_half_mirror row_mask:0xf bank_mask:0xf
	v_pk_mul_f32 v[20:21], v[20:21], v[164:165]
	v_add_f32_dpp v28, v28, v28 row_ror:8 row_mask:0xf bank_mask:0xf
	v_add_f32_dpp v32, v32, v32 row_ror:8 row_mask:0xf bank_mask:0xf
	v_pk_mul_f32 v[22:23], v[22:23], v[166:167]
	v_add_f32_dpp v28, v28, v28 quad_perm:[1,0,3,2] row_mask:0xf bank_mask:0xf
	v_add_f32_dpp v32, v32, v32 quad_perm:[1,0,3,2] row_mask:0xf bank_mask:0xf
	v_pk_mul_f32 v[24:25], v[24:25], v[164:165]
	v_add_f32_dpp v28, v28, v28 quad_perm:[2,3,0,1] row_mask:0xf bank_mask:0xf
	v_add_f32_dpp v32, v32, v32 quad_perm:[2,3,0,1] row_mask:0xf bank_mask:0xf
	v_pk_mul_f32 v[26:27], v[26:27], v[166:167]
	v_pk_fma_f32 v[20:21], v[176:177], v[4:5], v[20:21] op_sel_hi:[1,0,1]
	v_mov_b32_dpp v30, v28 row_half_mirror row_mask:0xf bank_mask:0xf
	v_pk_fma_f32 v[22:23], v[178:179], v[4:5], v[22:23] op_sel_hi:[1,0,1]
	v_pk_fma_f32 v[24:25], v[176:177], v[6:7], v[24:25] op_sel_hi:[1,0,1]
	v_pk_fma_f32 v[26:27], v[178:179], v[6:7], v[26:27] op_sel_hi:[1,0,1]
	v_pk_fma_f32 v[20:21], v[84:85], v[28:29], v[20:21] op_sel_hi:[1,0,1] neg_lo:[0,1,0] neg_hi:[0,1,0]
	v_pk_fma_f32 v[22:23], v[86:87], v[28:29], v[22:23] op_sel_hi:[1,0,1] neg_lo:[0,1,0] neg_hi:[0,1,0]
	v_pk_fma_f32 v[24:25], v[84:85], v[30:31], v[24:25] op_sel_hi:[1,0,1] neg_lo:[0,1,0] neg_hi:[0,1,0]
	v_pk_fma_f32 v[26:27], v[86:87], v[30:31], v[26:27] op_sel_hi:[1,0,1] neg_lo:[0,1,0] neg_hi:[0,1,0]
	v_add_f32_e32 v39, v32, v5
	ds_write_b32 v102, v39 offset:3840
	s_waitcnt lgkmcnt(2)
	v_mul_f32_e32 v34, v24, v144
	v_mul_f32_e32 v38, v24, v156
	v_mul_f32_e32 v33, v20, v144
	v_mul_f32_e32 v35, v20, v156
	v_fmac_f32_e32 v34, v25, v145
	v_fmac_f32_e32 v38, v25, v157
	v_fmac_f32_e32 v33, v21, v145
	v_fmac_f32_e32 v35, v21, v157
	v_fmac_f32_e32 v34, v26, v146
	v_fmac_f32_e32 v38, v26, v158
	v_fmac_f32_e32 v33, v22, v146
	v_fmac_f32_e32 v35, v22, v158
	v_fmac_f32_e32 v34, v27, v147
	v_fmac_f32_e32 v38, v27, v159
	v_fmac_f32_e32 v33, v23, v147
	v_fmac_f32_e32 v35, v23, v159
	v_add_f32_dpp v28, v34, v33 row_half_mirror row_mask:0xf bank_mask:0xf
	v_add_f32_dpp v32, v38, v35 row_half_mirror row_mask:0xf bank_mask:0xf
	v_pk_mul_f32 v[20:21], v[20:21], v[168:169]
	v_add_f32_dpp v28, v28, v28 row_ror:8 row_mask:0xf bank_mask:0xf
	v_add_f32_dpp v32, v32, v32 row_ror:8 row_mask:0xf bank_mask:0xf
	v_pk_mul_f32 v[22:23], v[22:23], v[170:171]
	v_add_f32_dpp v28, v28, v28 quad_perm:[1,0,3,2] row_mask:0xf bank_mask:0xf
	v_add_f32_dpp v32, v32, v32 quad_perm:[1,0,3,2] row_mask:0xf bank_mask:0xf
	v_pk_mul_f32 v[24:25], v[24:25], v[168:169]
	v_add_f32_dpp v28, v28, v28 quad_perm:[2,3,0,1] row_mask:0xf bank_mask:0xf
	v_add_f32_dpp v32, v32, v32 quad_perm:[2,3,0,1] row_mask:0xf bank_mask:0xf
	v_pk_mul_f32 v[26:27], v[26:27], v[170:171]
	v_pk_fma_f32 v[20:21], v[180:181], v[8:9], v[20:21] op_sel_hi:[1,0,1]
	v_mov_b32_dpp v30, v28 row_half_mirror row_mask:0xf bank_mask:0xf
	v_pk_fma_f32 v[22:23], v[182:183], v[8:9], v[22:23] op_sel_hi:[1,0,1]
	v_pk_fma_f32 v[24:25], v[180:181], v[10:11], v[24:25] op_sel_hi:[1,0,1]
	v_pk_fma_f32 v[26:27], v[182:183], v[10:11], v[26:27] op_sel_hi:[1,0,1]
	v_pk_fma_f32 v[20:21], v[88:89], v[28:29], v[20:21] op_sel_hi:[1,0,1] neg_lo:[0,1,0] neg_hi:[0,1,0]
	v_pk_fma_f32 v[22:23], v[90:91], v[28:29], v[22:23] op_sel_hi:[1,0,1] neg_lo:[0,1,0] neg_hi:[0,1,0]
	v_pk_fma_f32 v[24:25], v[88:89], v[30:31], v[24:25] op_sel_hi:[1,0,1] neg_lo:[0,1,0] neg_hi:[0,1,0]
	v_pk_fma_f32 v[26:27], v[90:91], v[30:31], v[26:27] op_sel_hi:[1,0,1] neg_lo:[0,1,0] neg_hi:[0,1,0]
	v_add_f32_e32 v39, v32, v9
	ds_write_b32 v102, v39 offset:3968
	s_waitcnt lgkmcnt(0)
	s_barrier
	s_add_i32 s8, s8, 1
	s_cmp_eq_u32 s8, 64
	s_cbranch_scc0 .Lrw_scan_loop
	s_setprio 0
	s_branch .LBB0_183
